# epilogue base-load hoisting also in the ffn1 down GEMM (f32 x base, two batches); 2 wait states before the v_mov over a just-issued store's data registers
# baseline (speedup 1.0000x reference)
; __device__ __forceinline__ unsigned cvt_pk_bf16(float lo, float hi) { unsigned r; asm volatile("v_cvt_pk_bf16_f32 %0, %1, %2" : "=v"(r) : "v"(lo), "v"(hi)); return r; }
;     __device__ __forceinline__ void operator()(const f32x4 (&acc)[2][2][4][2], const Unit& u, int wr, int wc, int fr, int fq) const {
;         const int row0 = u.pm * BM + wr * 64 + fr; const int col0 = u.pn * BM + wc * 32 + 8 * fq;
; #pragma unroll
;         for (int ai = 0; ai < 2; ++ai)
; #pragma unroll
;             for (int m = 0; m < 4; ++m) { const int row = row0 + ai * HALF + m * 16; const size_t off = (size_t)row * ldc + col0; float part = 0.f;
; #pragma unroll
;                 for (int bj = 0; bj < 2; ++bj) { const size_t idx = off + bj * HALF;
;                     f32x4 b0, b1;
;                     if constexpr (BASE_BF16) { const u32x4 r = *(const u32x4*)(baseb + idx);
;                         b0 = (f32x4){__builtin_bit_cast(float, r.x << 16), __builtin_bit_cast(float, r.x & 0xffff0000u), __builtin_bit_cast(float, r.y << 16), __builtin_bit_cast(float, r.y & 0xffff0000u)};
;                         b1 = (f32x4){__builtin_bit_cast(float, r.z << 16), __builtin_bit_cast(float, r.z & 0xffff0000u), __builtin_bit_cast(float, r.w << 16), __builtin_bit_cast(float, r.w & 0xffff0000u)}; }
;                     else { b0 = *(const f32x4*)(base + idx); b1 = *(const f32x4*)(base + idx + 4); }
;                     const f32x4 o0 = b0 + acc[ai][bj][m][0] * alpha, o1 = b1 + acc[ai][bj][m][1] * alpha;
;                     if constexpr (WRITE_F32) { *(f32x4*)(out + idx) = o0; *(f32x4*)(out + idx + 4) = o1; }
;                     if constexpr (WRITE_XB) {
;                         part += (o0[0] * o0[0] + o0[1] * o0[1]) + (o0[2] * o0[2] + o0[3] * o0[3]) + (o1[0] * o1[0] + o1[1] * o1[1]) + (o1[2] * o1[2] + o1[3] * o1[3]);
;                         u32x4 w; w.x = cvt_pk_bf16(o0[0], o0[1]); w.y = cvt_pk_bf16(o0[2], o0[3]); w.z = cvt_pk_bf16(o1[0], o1[1]); w.w = cvt_pk_bf16(o1[2], o1[3]);
;                         *(u32x4*)(xb + idx) = w; } }
;                 if constexpr (WRITE_XB) { part += __shfl_xor(part, 16); part += __shfl_xor(part, 32);
;                     if (fq == 0) atomicAdd(ss + row, part); } }
;     }
.LBB0_262:
	v_lshl_add_u32 v146, s28, 8, v148
	v_lshl_or_b32 v144, s29, 8, v150
	v_ashrrev_i32_e32 v147, 31, v146
	v_ashrrev_i32_e32 v145, 31, v144
	v_mov_b32_e32 v248, v146
	v_lshl_add_u32 v248, v248, 11, v144
	v_lshlrev_b32_e32 v248, 2, v248
	global_load_dwordx4 v[172:175], v248, s[52:53]
	global_load_dwordx4 v[176:179], v248, s[52:53] offset:16
	global_load_dwordx4 v[180:183], v248, s[52:53] offset:512
	global_load_dwordx4 v[184:187], v248, s[52:53] offset:528
	v_add_u32_e32 v249, 16, v146
	v_lshl_add_u32 v249, v249, 11, v144
	v_lshlrev_b32_e32 v249, 2, v249
	global_load_dwordx4 v[188:191], v249, s[52:53]
	global_load_dwordx4 v[192:195], v249, s[52:53] offset:16
	global_load_dwordx4 v[196:199], v249, s[52:53] offset:512
	global_load_dwordx4 v[200:203], v249, s[52:53] offset:528
	v_add_u32_e32 v250, 32, v146
	v_lshl_add_u32 v250, v250, 11, v144
	v_lshlrev_b32_e32 v250, 2, v250
	global_load_dwordx4 v[204:207], v250, s[52:53]
	global_load_dwordx4 v[208:211], v250, s[52:53] offset:16
	global_load_dwordx4 v[212:215], v250, s[52:53] offset:512
	global_load_dwordx4 v[220:223], v250, s[52:53] offset:528
	v_add_u32_e32 v251, 48, v146
	v_lshl_add_u32 v251, v251, 11, v144
	v_lshlrev_b32_e32 v251, 2, v251
	global_load_dwordx4 v[224:227], v251, s[52:53]
	global_load_dwordx4 v[228:231], v251, s[52:53] offset:16
	global_load_dwordx4 v[232:235], v251, s[52:53] offset:512
	global_load_dwordx4 v[236:239], v251, s[52:53] offset:528
	v_lshlrev_b64 v[156:157], 11, v[146:147]
	v_lshl_add_u64 v[164:165], v[156:157], 0, v[144:145]
	v_lshl_add_u64 v[166:167], v[164:165], 2, s[52:53]
	s_waitcnt vmcnt(15)
	s_nop 1
	v_mov_b32_e32 v156, v172
	v_mov_b32_e32 v157, v173
	v_mov_b32_e32 v158, v174
	v_mov_b32_e32 v159, v175
	s_waitcnt vmcnt(14)
	s_nop 1
	v_mov_b32_e32 v160, v176
	v_mov_b32_e32 v161, v177
	v_mov_b32_e32 v162, v178
	v_mov_b32_e32 v163, v179
	v_lshlrev_b64 v[164:165], 1, v[164:165]
	v_lshl_add_u64 v[168:169], s[16:17], 0, v[164:165]
	v_xor_b32_e32 v155, 32, v154
	v_or_b32_e32 v164, 0x100, v164
	v_pk_fma_f32 v[126:127], v[126:127], 0.5, v[158:159] op_sel_hi:[1,0,1]
	v_pk_fma_f32 v[170:171], v[124:125], 0.5, v[156:157] op_sel_hi:[1,0,1]
	v_pk_fma_f32 v[162:163], v[122:123], 0.5, v[162:163] op_sel_hi:[1,0,1]
	v_pk_fma_f32 v[160:161], v[120:121], 0.5, v[160:161] op_sel_hi:[1,0,1]
	v_cvt_pk_bf16_f32 v120, v170, v171
	v_cvt_pk_bf16_f32 v121, v126, v127
	v_mul_f32_e32 v127, v127, v127
	v_cvt_pk_bf16_f32 v122, v160, v161
	v_cvt_pk_bf16_f32 v123, v162, v163
	global_store_dwordx4 v[168:169], v[120:123], off
	s_waitcnt vmcnt(13)
	s_nop 1
	v_mov_b32_e32 v122, v180
	v_mov_b32_e32 v123, v181
	v_mov_b32_e32 v124, v182
	v_mov_b32_e32 v125, v183
	s_nop 0
	s_waitcnt vmcnt(12)
	s_nop 1
	v_mov_b32_e32 v156, v184
	v_mov_b32_e32 v157, v185
	v_mov_b32_e32 v158, v186
	v_mov_b32_e32 v159, v187
	v_mul_f32_e32 v166, v171, v171
	v_and_b32_e32 v121, 64, v154
	v_mul_f32_e32 v161, v161, v161
	v_fmac_f32_e32 v166, v170, v170
	v_fmac_f32_e32 v127, v126, v126
	v_xor_b32_e32 v120, 16, v154
	v_add_u32_e32 v121, 64, v121
	v_mul_f32_e32 v163, v163, v163
	v_fmac_f32_e32 v161, v160, v160
	v_add_f32_e32 v126, v166, v127
	v_cmp_lt_i32_e32 vcc, v120, v121
	v_fmac_f32_e32 v163, v162, v162
	v_add_f32_e32 v126, v161, v126
	v_cndmask_b32_e32 v120, v154, v120, vcc
	v_add_f32_e32 v126, v163, v126
	v_lshlrev_b32_e32 v120, 2, v120
	v_cmp_lt_i32_e32 vcc, v155, v121
	v_pk_fma_f32 v[118:119], v[118:119], 0.5, v[124:125] op_sel_hi:[1,0,1]
	v_pk_fma_f32 v[116:117], v[116:117], 0.5, v[122:123] op_sel_hi:[1,0,1]
	v_pk_fma_f32 v[122:123], v[114:115], 0.5, v[158:159] op_sel_hi:[1,0,1]
	v_pk_fma_f32 v[112:113], v[112:113], 0.5, v[156:157] op_sel_hi:[1,0,1]
	v_mul_f32_e32 v114, v117, v117
	v_mul_f32_e32 v115, v119, v119
	v_mul_f32_e32 v124, v113, v113
	v_fmac_f32_e32 v114, v116, v116
	v_fmac_f32_e32 v115, v118, v118
	v_mul_f32_e32 v125, v123, v123
	v_fmac_f32_e32 v124, v112, v112
	v_add_f32_e32 v114, v114, v115
	v_fmac_f32_e32 v125, v122, v122
	v_add_f32_e32 v114, v124, v114
	v_add_f32_e32 v114, v125, v114
	v_add_f32_e32 v114, v126, v114
	ds_bpermute_b32 v115, v120, v114
	v_cndmask_b32_e32 v121, v154, v155, vcc
	v_cvt_pk_bf16_f32 v116, v116, v117
	v_cvt_pk_bf16_f32 v117, v118, v119
	v_cvt_pk_bf16_f32 v118, v112, v113
	s_waitcnt lgkmcnt(0)
	v_add_f32_e32 v112, v114, v115
	v_lshlrev_b32_e32 v114, 2, v121
	ds_bpermute_b32 v113, v114, v112
	v_cvt_pk_bf16_f32 v119, v122, v123
	v_lshl_add_u64 v[122:123], s[16:17], 0, v[164:165]
	global_store_dwordx4 v[122:123], v[116:119], off
	s_and_saveexec_b64 s[46:47], s[2:3]
	s_cbranch_execz .LBB0_264
	v_lshl_add_u64 v[116:117], v[146:147], 2, s[18:19]
	s_waitcnt lgkmcnt(0)
	v_add_f32_e32 v112, v112, v113
	global_atomic_add_f32 v[116:117], v112, off
; __device__ __forceinline__ unsigned cvt_pk_bf16(float lo, float hi) { unsigned r; asm volatile("v_cvt_pk_bf16_f32 %0, %1, %2" : "=v"(r) : "v"(lo), "v"(hi)); return r; }
;     __device__ __forceinline__ void operator()(const f32x4 (&acc)[2][2][4][2], const Unit& u, int wr, int wc, int fr, int fq) const {
;         const int row0 = u.pm * BM + wr * 64 + fr; const int col0 = u.pn * BM + wc * 32 + 8 * fq;
; #pragma unroll
;         for (int ai = 0; ai < 2; ++ai)
; #pragma unroll
;             for (int m = 0; m < 4; ++m) { const int row = row0 + ai * HALF + m * 16; const size_t off = (size_t)row * ldc + col0; float part = 0.f;
; #pragma unroll
;                 for (int bj = 0; bj < 2; ++bj) { const size_t idx = off + bj * HALF;
;                     f32x4 b0, b1;
;                     if constexpr (BASE_BF16) { const u32x4 r = *(const u32x4*)(baseb + idx);
;                         b0 = (f32x4){__builtin_bit_cast(float, r.x << 16), __builtin_bit_cast(float, r.x & 0xffff0000u), __builtin_bit_cast(float, r.y << 16), __builtin_bit_cast(float, r.y & 0xffff0000u)};
;                         b1 = (f32x4){__builtin_bit_cast(float, r.z << 16), __builtin_bit_cast(float, r.z & 0xffff0000u), __builtin_bit_cast(float, r.w << 16), __builtin_bit_cast(float, r.w & 0xffff0000u)}; }
;                     else { b0 = *(const f32x4*)(base + idx); b1 = *(const f32x4*)(base + idx + 4); }
;                     const f32x4 o0 = b0 + acc[ai][bj][m][0] * alpha, o1 = b1 + acc[ai][bj][m][1] * alpha;
;                     if constexpr (WRITE_F32) { *(f32x4*)(out + idx) = o0; *(f32x4*)(out + idx + 4) = o1; }
;                     if constexpr (WRITE_XB) {
;                         part += (o0[0] * o0[0] + o0[1] * o0[1]) + (o0[2] * o0[2] + o0[3] * o0[3]) + (o1[0] * o1[0] + o1[1] * o1[1]) + (o1[2] * o1[2] + o1[3] * o1[3]);
;                         u32x4 w; w.x = cvt_pk_bf16(o0[0], o0[1]); w.y = cvt_pk_bf16(o0[2], o0[3]); w.z = cvt_pk_bf16(o1[0], o1[1]); w.w = cvt_pk_bf16(o1[2], o1[3]);
;                         *(u32x4*)(xb + idx) = w; } }
;                 if constexpr (WRITE_XB) { part += __shfl_xor(part, 16); part += __shfl_xor(part, 32);
;                     if (fq == 0) atomicAdd(ss + row, part); } }
;     }
.LBB0_264:
	s_or_b64 exec, exec, s[46:47]
	v_or_b32_e32 v112, 16, v146
	s_waitcnt lgkmcnt(0)
	v_ashrrev_i32_e32 v113, 31, v112
	v_lshlrev_b64 v[116:117], 11, v[112:113]
	v_lshl_add_u64 v[126:127], v[116:117], 0, v[144:145]
	v_lshl_add_u64 v[156:157], v[126:127], 2, s[52:53]
	s_waitcnt vmcnt(11)
	s_nop 1
	v_mov_b32_e32 v116, v188
	v_mov_b32_e32 v117, v189
	v_mov_b32_e32 v118, v190
	v_mov_b32_e32 v119, v191
	s_waitcnt vmcnt(10)
	s_nop 1
	v_mov_b32_e32 v122, v192
	v_mov_b32_e32 v123, v193
	v_mov_b32_e32 v124, v194
	v_mov_b32_e32 v125, v195
	v_lshlrev_b64 v[126:127], 1, v[126:127]
	v_lshl_add_u64 v[158:159], s[16:17], 0, v[126:127]
	v_or_b32_e32 v126, 0x100, v126
	v_pk_fma_f32 v[118:119], v[110:111], 0.5, v[118:119] op_sel_hi:[1,0,1]
	v_pk_fma_f32 v[116:117], v[108:109], 0.5, v[116:117] op_sel_hi:[1,0,1]
	v_pk_fma_f32 v[124:125], v[106:107], 0.5, v[124:125] op_sel_hi:[1,0,1]
	v_pk_fma_f32 v[122:123], v[104:105], 0.5, v[122:123] op_sel_hi:[1,0,1]
	v_cvt_pk_bf16_f32 v104, v116, v117
	v_cvt_pk_bf16_f32 v105, v118, v119
	v_mul_f32_e32 v115, v117, v117
	v_cvt_pk_bf16_f32 v106, v122, v123
	v_cvt_pk_bf16_f32 v107, v124, v125
	global_store_dwordx4 v[158:159], v[104:107], off
	s_waitcnt vmcnt(9)
	s_nop 1
	v_mov_b32_e32 v104, v196
	v_mov_b32_e32 v105, v197
	v_mov_b32_e32 v106, v198
	v_mov_b32_e32 v107, v199
	s_nop 0
	s_waitcnt vmcnt(8)
	s_nop 1
	v_mov_b32_e32 v108, v200
	v_mov_b32_e32 v109, v201
	v_mov_b32_e32 v110, v202
	v_mov_b32_e32 v111, v203
	v_mul_f32_e32 v117, v119, v119
	v_mul_f32_e32 v119, v123, v123
	v_fmac_f32_e32 v115, v116, v116
	v_fmac_f32_e32 v117, v118, v118
	v_mul_f32_e32 v121, v125, v125
	v_fmac_f32_e32 v119, v122, v122
	v_add_f32_e32 v115, v115, v117
	v_fmac_f32_e32 v121, v124, v124
	v_add_f32_e32 v115, v119, v115
	v_add_f32_e32 v115, v121, v115
	v_pk_fma_f32 v[102:103], v[102:103], 0.5, v[106:107] op_sel_hi:[1,0,1]
	v_pk_fma_f32 v[100:101], v[100:101], 0.5, v[104:105] op_sel_hi:[1,0,1]
	v_pk_fma_f32 v[104:105], v[98:99], 0.5, v[110:111] op_sel_hi:[1,0,1]
	v_pk_fma_f32 v[96:97], v[96:97], 0.5, v[108:109] op_sel_hi:[1,0,1]
	v_mul_f32_e32 v98, v101, v101
	v_mul_f32_e32 v99, v103, v103
	v_mul_f32_e32 v106, v97, v97
	v_fmac_f32_e32 v98, v100, v100
	v_fmac_f32_e32 v99, v102, v102
	v_mul_f32_e32 v107, v105, v105
	v_fmac_f32_e32 v106, v96, v96
	v_add_f32_e32 v98, v98, v99
	v_add_f32_e32 v98, v106, v98
	v_fmac_f32_e32 v107, v104, v104
	v_add_f32_e32 v98, v107, v98
	v_add_f32_e32 v106, v115, v98
	ds_bpermute_b32 v107, v120, v106
	v_cvt_pk_bf16_f32 v98, v100, v101
	v_cvt_pk_bf16_f32 v99, v102, v103
	v_cvt_pk_bf16_f32 v100, v96, v97
	v_lshl_add_u64 v[102:103], s[16:17], 0, v[126:127]
	s_waitcnt lgkmcnt(0)
	v_add_f32_e32 v96, v106, v107
	ds_bpermute_b32 v97, v114, v96
	v_cvt_pk_bf16_f32 v101, v104, v105
	global_store_dwordx4 v[102:103], v[98:101], off
	s_and_saveexec_b64 s[46:47], s[2:3]
	s_cbranch_execz .LBB0_266
	v_lshl_add_u64 v[98:99], v[112:113], 2, s[18:19]
	s_waitcnt lgkmcnt(0)
	v_add_f32_e32 v96, v96, v97
	global_atomic_add_f32 v[98:99], v96, off
.LBB0_266:
	s_or_b64 exec, exec, s[46:47]
	v_or_b32_e32 v96, 32, v146
	s_waitcnt lgkmcnt(0)
	v_ashrrev_i32_e32 v97, 31, v96
	v_lshlrev_b64 v[98:99], 11, v[96:97]
	v_lshl_add_u64 v[106:107], v[98:99], 0, v[144:145]
	v_lshl_add_u64 v[108:109], v[106:107], 2, s[52:53]
	s_waitcnt vmcnt(7)
	s_nop 1
	v_mov_b32_e32 v98, v204
	v_mov_b32_e32 v99, v205
	v_mov_b32_e32 v100, v206
	v_mov_b32_e32 v101, v207
	s_waitcnt vmcnt(6)
	s_nop 1
	v_mov_b32_e32 v102, v208
	v_mov_b32_e32 v103, v209
	v_mov_b32_e32 v104, v210
	v_mov_b32_e32 v105, v211
	v_lshlrev_b64 v[106:107], 1, v[106:107]
	v_lshl_add_u64 v[110:111], s[16:17], 0, v[106:107]
	v_or_b32_e32 v106, 0x100, v106
	v_pk_fma_f32 v[100:101], v[94:95], 0.5, v[100:101] op_sel_hi:[1,0,1]
	v_pk_fma_f32 v[98:99], v[92:93], 0.5, v[98:99] op_sel_hi:[1,0,1]
	v_pk_fma_f32 v[104:105], v[90:91], 0.5, v[104:105] op_sel_hi:[1,0,1]
	v_pk_fma_f32 v[102:103], v[88:89], 0.5, v[102:103] op_sel_hi:[1,0,1]
	v_cvt_pk_bf16_f32 v88, v98, v99
	v_cvt_pk_bf16_f32 v89, v100, v101
	v_mul_f32_e32 v99, v99, v99
	v_cvt_pk_bf16_f32 v90, v102, v103
	v_cvt_pk_bf16_f32 v91, v104, v105
	global_store_dwordx4 v[110:111], v[88:91], off
	s_waitcnt vmcnt(5)
	s_nop 1
	v_mov_b32_e32 v88, v212
	v_mov_b32_e32 v89, v213
	v_mov_b32_e32 v90, v214
	v_mov_b32_e32 v91, v215
	s_nop 0
	s_waitcnt vmcnt(4)
	s_nop 1
	v_mov_b32_e32 v92, v220
	v_mov_b32_e32 v93, v221
	v_mov_b32_e32 v94, v222
	v_mov_b32_e32 v95, v223
	v_mul_f32_e32 v101, v101, v101
	v_mul_f32_e32 v103, v103, v103
	v_fmac_f32_e32 v99, v98, v98
	v_fmac_f32_e32 v101, v100, v100
	v_mul_f32_e32 v105, v105, v105
	v_fmac_f32_e32 v103, v102, v102
	v_add_f32_e32 v98, v99, v101
	v_fmac_f32_e32 v105, v104, v104
	v_add_f32_e32 v98, v103, v98
	v_add_f32_e32 v98, v105, v98
	v_pk_fma_f32 v[86:87], v[86:87], 0.5, v[90:91] op_sel_hi:[1,0,1]
	v_pk_fma_f32 v[84:85], v[84:85], 0.5, v[88:89] op_sel_hi:[1,0,1]
	v_pk_fma_f32 v[88:89], v[82:83], 0.5, v[94:95] op_sel_hi:[1,0,1]
	v_pk_fma_f32 v[80:81], v[80:81], 0.5, v[92:93] op_sel_hi:[1,0,1]
	v_mul_f32_e32 v82, v85, v85
	v_mul_f32_e32 v83, v87, v87
	v_mul_f32_e32 v90, v81, v81
	v_fmac_f32_e32 v82, v84, v84
	v_fmac_f32_e32 v83, v86, v86
	v_mul_f32_e32 v91, v89, v89
	v_fmac_f32_e32 v90, v80, v80
	v_add_f32_e32 v82, v82, v83
	v_add_f32_e32 v82, v90, v82
	v_fmac_f32_e32 v91, v88, v88
	v_add_f32_e32 v82, v91, v82
	v_add_f32_e32 v90, v98, v82
	ds_bpermute_b32 v91, v120, v90
	v_cvt_pk_bf16_f32 v82, v84, v85
	v_cvt_pk_bf16_f32 v83, v86, v87
	v_cvt_pk_bf16_f32 v84, v80, v81
	v_lshl_add_u64 v[86:87], s[16:17], 0, v[106:107]
	s_waitcnt lgkmcnt(0)
	v_add_f32_e32 v80, v90, v91
	ds_bpermute_b32 v81, v114, v80
	v_cvt_pk_bf16_f32 v85, v88, v89
	global_store_dwordx4 v[86:87], v[82:85], off
	s_and_saveexec_b64 s[46:47], s[2:3]
	s_cbranch_execz .LBB0_268
	v_lshl_add_u64 v[82:83], v[96:97], 2, s[18:19]
	s_waitcnt lgkmcnt(0)
	v_add_f32_e32 v80, v80, v81
	global_atomic_add_f32 v[82:83], v80, off
; __device__ __forceinline__ unsigned cvt_pk_bf16(float lo, float hi) { unsigned r; asm volatile("v_cvt_pk_bf16_f32 %0, %1, %2" : "=v"(r) : "v"(lo), "v"(hi)); return r; }
;     __device__ __forceinline__ void operator()(const f32x4 (&acc)[2][2][4][2], const Unit& u, int wr, int wc, int fr, int fq) const {
;         const int row0 = u.pm * BM + wr * 64 + fr; const int col0 = u.pn * BM + wc * 32 + 8 * fq;
; #pragma unroll
;         for (int ai = 0; ai < 2; ++ai)
; #pragma unroll
;             for (int m = 0; m < 4; ++m) { const int row = row0 + ai * HALF + m * 16; const size_t off = (size_t)row * ldc + col0; float part = 0.f;
; #pragma unroll
;                 for (int bj = 0; bj < 2; ++bj) { const size_t idx = off + bj * HALF;
;                     f32x4 b0, b1;
;                     if constexpr (BASE_BF16) { const u32x4 r = *(const u32x4*)(baseb + idx);
;                         b0 = (f32x4){__builtin_bit_cast(float, r.x << 16), __builtin_bit_cast(float, r.x & 0xffff0000u), __builtin_bit_cast(float, r.y << 16), __builtin_bit_cast(float, r.y & 0xffff0000u)};
;                         b1 = (f32x4){__builtin_bit_cast(float, r.z << 16), __builtin_bit_cast(float, r.z & 0xffff0000u), __builtin_bit_cast(float, r.w << 16), __builtin_bit_cast(float, r.w & 0xffff0000u)}; }
;                     else { b0 = *(const f32x4*)(base + idx); b1 = *(const f32x4*)(base + idx + 4); }
;                     const f32x4 o0 = b0 + acc[ai][bj][m][0] * alpha, o1 = b1 + acc[ai][bj][m][1] * alpha;
;                     if constexpr (WRITE_F32) { *(f32x4*)(out + idx) = o0; *(f32x4*)(out + idx + 4) = o1; }
;                     if constexpr (WRITE_XB) {
;                         part += (o0[0] * o0[0] + o0[1] * o0[1]) + (o0[2] * o0[2] + o0[3] * o0[3]) + (o1[0] * o1[0] + o1[1] * o1[1]) + (o1[2] * o1[2] + o1[3] * o1[3]);
;                         u32x4 w; w.x = cvt_pk_bf16(o0[0], o0[1]); w.y = cvt_pk_bf16(o0[2], o0[3]); w.z = cvt_pk_bf16(o1[0], o1[1]); w.w = cvt_pk_bf16(o1[2], o1[3]);
;                         *(u32x4*)(xb + idx) = w; } }
;                 if constexpr (WRITE_XB) { part += __shfl_xor(part, 16); part += __shfl_xor(part, 32);
;                     if (fq == 0) atomicAdd(ss + row, part); } }
;     }
.LBB0_268:
	s_or_b64 exec, exec, s[46:47]
	v_or_b32_e32 v80, 48, v146
	s_waitcnt lgkmcnt(0)
	v_ashrrev_i32_e32 v81, 31, v80
	v_lshlrev_b64 v[82:83], 11, v[80:81]
	v_lshl_add_u64 v[90:91], v[82:83], 0, v[144:145]
	v_lshl_add_u64 v[92:93], v[90:91], 2, s[52:53]
	s_waitcnt vmcnt(3)
	s_nop 1
	v_mov_b32_e32 v82, v224
	v_mov_b32_e32 v83, v225
	v_mov_b32_e32 v84, v226
	v_mov_b32_e32 v85, v227
	s_waitcnt vmcnt(2)
	s_nop 1
	v_mov_b32_e32 v86, v228
	v_mov_b32_e32 v87, v229
	v_mov_b32_e32 v88, v230
	v_mov_b32_e32 v89, v231
	v_lshlrev_b64 v[90:91], 1, v[90:91]
	v_lshl_add_u64 v[94:95], s[16:17], 0, v[90:91]
	v_or_b32_e32 v90, 0x100, v90
	v_pk_fma_f32 v[84:85], v[78:79], 0.5, v[84:85] op_sel_hi:[1,0,1]
	v_pk_fma_f32 v[82:83], v[76:77], 0.5, v[82:83] op_sel_hi:[1,0,1]
	v_pk_fma_f32 v[88:89], v[74:75], 0.5, v[88:89] op_sel_hi:[1,0,1]
	v_pk_fma_f32 v[86:87], v[72:73], 0.5, v[86:87] op_sel_hi:[1,0,1]
	v_cvt_pk_bf16_f32 v72, v82, v83
	v_cvt_pk_bf16_f32 v73, v84, v85
	v_mul_f32_e32 v83, v83, v83
	v_cvt_pk_bf16_f32 v74, v86, v87
	v_cvt_pk_bf16_f32 v75, v88, v89
	global_store_dwordx4 v[94:95], v[72:75], off
	s_waitcnt vmcnt(1)
	s_nop 1
	v_mov_b32_e32 v72, v232
	v_mov_b32_e32 v73, v233
	v_mov_b32_e32 v74, v234
	v_mov_b32_e32 v75, v235
	s_nop 0
	s_waitcnt vmcnt(0)
	s_nop 1
	v_mov_b32_e32 v76, v236
	v_mov_b32_e32 v77, v237
	v_mov_b32_e32 v78, v238
	v_mov_b32_e32 v79, v239
	v_add_u32_e32 v248, 0x80, v146
	v_lshl_add_u32 v248, v248, 11, v144
	v_lshlrev_b32_e32 v248, 2, v248
	global_load_dwordx4 v[172:175], v248, s[52:53]
	global_load_dwordx4 v[176:179], v248, s[52:53] offset:16
	global_load_dwordx4 v[180:183], v248, s[52:53] offset:512
	global_load_dwordx4 v[184:187], v248, s[52:53] offset:528
	v_add_u32_e32 v249, 0x90, v146
	v_lshl_add_u32 v249, v249, 11, v144
	v_lshlrev_b32_e32 v249, 2, v249
	global_load_dwordx4 v[188:191], v249, s[52:53]
	global_load_dwordx4 v[192:195], v249, s[52:53] offset:16
	global_load_dwordx4 v[196:199], v249, s[52:53] offset:512
	global_load_dwordx4 v[200:203], v249, s[52:53] offset:528
	v_add_u32_e32 v250, 0xa0, v146
	v_lshl_add_u32 v250, v250, 11, v144
	v_lshlrev_b32_e32 v250, 2, v250
	global_load_dwordx4 v[204:207], v250, s[52:53]
	global_load_dwordx4 v[208:211], v250, s[52:53] offset:16
	global_load_dwordx4 v[212:215], v250, s[52:53] offset:512
	global_load_dwordx4 v[220:223], v250, s[52:53] offset:528
	v_add_u32_e32 v251, 0xb0, v146
	v_lshl_add_u32 v251, v251, 11, v144
	v_lshlrev_b32_e32 v251, 2, v251
	global_load_dwordx4 v[224:227], v251, s[52:53]
	global_load_dwordx4 v[228:231], v251, s[52:53] offset:16
	global_load_dwordx4 v[232:235], v251, s[52:53] offset:512
	global_load_dwordx4 v[236:239], v251, s[52:53] offset:528
	v_mul_f32_e32 v85, v85, v85
	v_mul_f32_e32 v87, v87, v87
	v_fmac_f32_e32 v83, v82, v82
	v_fmac_f32_e32 v85, v84, v84
	v_mul_f32_e32 v89, v89, v89
	v_fmac_f32_e32 v87, v86, v86
	v_add_f32_e32 v82, v83, v85
	v_fmac_f32_e32 v89, v88, v88
	v_add_f32_e32 v82, v87, v82
	v_add_f32_e32 v82, v89, v82
	v_pk_fma_f32 v[70:71], v[70:71], 0.5, v[74:75] op_sel_hi:[1,0,1]
	v_pk_fma_f32 v[68:69], v[68:69], 0.5, v[72:73] op_sel_hi:[1,0,1]
	v_pk_fma_f32 v[72:73], v[66:67], 0.5, v[78:79] op_sel_hi:[1,0,1]
	v_pk_fma_f32 v[64:65], v[64:65], 0.5, v[76:77] op_sel_hi:[1,0,1]
	v_mul_f32_e32 v66, v69, v69
	v_mul_f32_e32 v67, v71, v71
	v_mul_f32_e32 v74, v65, v65
	v_fmac_f32_e32 v66, v68, v68
	v_fmac_f32_e32 v67, v70, v70
	v_mul_f32_e32 v75, v73, v73
	v_fmac_f32_e32 v74, v64, v64
	v_add_f32_e32 v66, v66, v67
	v_add_f32_e32 v66, v74, v66
	v_fmac_f32_e32 v75, v72, v72
	v_add_f32_e32 v66, v75, v66
	v_add_f32_e32 v74, v82, v66
	ds_bpermute_b32 v75, v120, v74
	v_cvt_pk_bf16_f32 v66, v68, v69
	v_cvt_pk_bf16_f32 v67, v70, v71
	v_cvt_pk_bf16_f32 v68, v64, v65
	v_lshl_add_u64 v[70:71], s[16:17], 0, v[90:91]
	s_waitcnt lgkmcnt(0)
	v_add_f32_e32 v64, v74, v75
	ds_bpermute_b32 v65, v114, v64
	v_cvt_pk_bf16_f32 v69, v72, v73
	global_store_dwordx4 v[70:71], v[66:69], off
	s_and_saveexec_b64 s[46:47], s[2:3]
	s_cbranch_execz .LBB0_270
	v_lshl_add_u64 v[66:67], v[80:81], 2, s[18:19]
	s_waitcnt lgkmcnt(0)
	v_add_f32_e32 v64, v64, v65
	global_atomic_add_f32 v[66:67], v64, off
.LBB0_270:
	s_or_b64 exec, exec, s[46:47]
	v_add_u32_e32 v64, 0x80, v146
	s_waitcnt lgkmcnt(0)
	v_ashrrev_i32_e32 v65, 31, v64
	v_lshlrev_b64 v[66:67], 11, v[64:65]
	v_lshl_add_u64 v[74:75], v[66:67], 0, v[144:145]
	v_lshl_add_u64 v[76:77], v[74:75], 2, s[52:53]
	s_waitcnt vmcnt(15)
	s_nop 1
	v_mov_b32_e32 v66, v172
	v_mov_b32_e32 v67, v173
	v_mov_b32_e32 v68, v174
	v_mov_b32_e32 v69, v175
	s_waitcnt vmcnt(14)
	s_nop 1
	v_mov_b32_e32 v70, v176
	v_mov_b32_e32 v71, v177
	v_mov_b32_e32 v72, v178
	v_mov_b32_e32 v73, v179
	v_lshlrev_b64 v[74:75], 1, v[74:75]
	v_lshl_add_u64 v[78:79], s[16:17], 0, v[74:75]
	v_or_b32_e32 v74, 0x100, v74
	v_pk_fma_f32 v[68:69], v[62:63], 0.5, v[68:69] op_sel_hi:[1,0,1]
	v_pk_fma_f32 v[66:67], v[60:61], 0.5, v[66:67] op_sel_hi:[1,0,1]
	v_pk_fma_f32 v[72:73], v[58:59], 0.5, v[72:73] op_sel_hi:[1,0,1]
	v_pk_fma_f32 v[70:71], v[56:57], 0.5, v[70:71] op_sel_hi:[1,0,1]
	v_cvt_pk_bf16_f32 v56, v66, v67
	v_cvt_pk_bf16_f32 v57, v68, v69
	v_mul_f32_e32 v67, v67, v67
	v_cvt_pk_bf16_f32 v58, v70, v71
	v_cvt_pk_bf16_f32 v59, v72, v73
	global_store_dwordx4 v[78:79], v[56:59], off
	s_waitcnt vmcnt(13)
	s_nop 1
	v_mov_b32_e32 v56, v180
	v_mov_b32_e32 v57, v181
	v_mov_b32_e32 v58, v182
	v_mov_b32_e32 v59, v183
	s_nop 0
	s_waitcnt vmcnt(12)
	s_nop 1
	v_mov_b32_e32 v60, v184
	v_mov_b32_e32 v61, v185
	v_mov_b32_e32 v62, v186
	v_mov_b32_e32 v63, v187
	v_mul_f32_e32 v69, v69, v69
	v_mul_f32_e32 v71, v71, v71
	v_fmac_f32_e32 v67, v66, v66
	v_fmac_f32_e32 v69, v68, v68
	v_mul_f32_e32 v73, v73, v73
	v_fmac_f32_e32 v71, v70, v70
	v_add_f32_e32 v66, v67, v69
	v_fmac_f32_e32 v73, v72, v72
	v_add_f32_e32 v66, v71, v66
	v_add_f32_e32 v66, v73, v66
	v_pk_fma_f32 v[54:55], v[54:55], 0.5, v[58:59] op_sel_hi:[1,0,1]
	v_pk_fma_f32 v[52:53], v[52:53], 0.5, v[56:57] op_sel_hi:[1,0,1]
	v_pk_fma_f32 v[56:57], v[50:51], 0.5, v[62:63] op_sel_hi:[1,0,1]
	v_pk_fma_f32 v[48:49], v[48:49], 0.5, v[60:61] op_sel_hi:[1,0,1]
	v_mul_f32_e32 v50, v53, v53
	v_mul_f32_e32 v51, v55, v55
	v_mul_f32_e32 v58, v49, v49
	v_fmac_f32_e32 v50, v52, v52
	v_fmac_f32_e32 v51, v54, v54
	v_mul_f32_e32 v59, v57, v57
	v_fmac_f32_e32 v58, v48, v48
	v_add_f32_e32 v50, v50, v51
	v_add_f32_e32 v50, v58, v50
	v_fmac_f32_e32 v59, v56, v56
	v_add_f32_e32 v50, v59, v50
	v_add_f32_e32 v58, v66, v50
	ds_bpermute_b32 v59, v120, v58
	v_cvt_pk_bf16_f32 v50, v52, v53
	v_cvt_pk_bf16_f32 v51, v54, v55
	v_cvt_pk_bf16_f32 v52, v48, v49
	v_lshl_add_u64 v[54:55], s[16:17], 0, v[74:75]
	s_waitcnt lgkmcnt(0)
	v_add_f32_e32 v48, v58, v59
	ds_bpermute_b32 v49, v114, v48
	v_cvt_pk_bf16_f32 v53, v56, v57
	global_store_dwordx4 v[54:55], v[50:53], off
	s_and_saveexec_b64 s[46:47], s[2:3]
	s_cbranch_execz .LBB0_272
	v_lshl_add_u64 v[50:51], v[64:65], 2, s[18:19]
	s_waitcnt lgkmcnt(0)
	v_add_f32_e32 v48, v48, v49
	global_atomic_add_f32 v[50:51], v48, off
; __device__ __forceinline__ unsigned cvt_pk_bf16(float lo, float hi) { unsigned r; asm volatile("v_cvt_pk_bf16_f32 %0, %1, %2" : "=v"(r) : "v"(lo), "v"(hi)); return r; }
;     __device__ __forceinline__ void operator()(const f32x4 (&acc)[2][2][4][2], const Unit& u, int wr, int wc, int fr, int fq) const {
;         const int row0 = u.pm * BM + wr * 64 + fr; const int col0 = u.pn * BM + wc * 32 + 8 * fq;
; #pragma unroll
;         for (int ai = 0; ai < 2; ++ai)
; #pragma unroll
;             for (int m = 0; m < 4; ++m) { const int row = row0 + ai * HALF + m * 16; const size_t off = (size_t)row * ldc + col0; float part = 0.f;
; #pragma unroll
;                 for (int bj = 0; bj < 2; ++bj) { const size_t idx = off + bj * HALF;
;                     f32x4 b0, b1;
;                     if constexpr (BASE_BF16) { const u32x4 r = *(const u32x4*)(baseb + idx);
;                         b0 = (f32x4){__builtin_bit_cast(float, r.x << 16), __builtin_bit_cast(float, r.x & 0xffff0000u), __builtin_bit_cast(float, r.y << 16), __builtin_bit_cast(float, r.y & 0xffff0000u)};
;                         b1 = (f32x4){__builtin_bit_cast(float, r.z << 16), __builtin_bit_cast(float, r.z & 0xffff0000u), __builtin_bit_cast(float, r.w << 16), __builtin_bit_cast(float, r.w & 0xffff0000u)}; }
;                     else { b0 = *(const f32x4*)(base + idx); b1 = *(const f32x4*)(base + idx + 4); }
;                     const f32x4 o0 = b0 + acc[ai][bj][m][0] * alpha, o1 = b1 + acc[ai][bj][m][1] * alpha;
;                     if constexpr (WRITE_F32) { *(f32x4*)(out + idx) = o0; *(f32x4*)(out + idx + 4) = o1; }
;                     if constexpr (WRITE_XB) {
;                         part += (o0[0] * o0[0] + o0[1] * o0[1]) + (o0[2] * o0[2] + o0[3] * o0[3]) + (o1[0] * o1[0] + o1[1] * o1[1]) + (o1[2] * o1[2] + o1[3] * o1[3]);
;                         u32x4 w; w.x = cvt_pk_bf16(o0[0], o0[1]); w.y = cvt_pk_bf16(o0[2], o0[3]); w.z = cvt_pk_bf16(o1[0], o1[1]); w.w = cvt_pk_bf16(o1[2], o1[3]);
;                         *(u32x4*)(xb + idx) = w; } }
;                 if constexpr (WRITE_XB) { part += __shfl_xor(part, 16); part += __shfl_xor(part, 32);
;                     if (fq == 0) atomicAdd(ss + row, part); } }
;     }
.LBB0_272:
	s_or_b64 exec, exec, s[46:47]
	v_add_u32_e32 v48, 0x90, v146
	s_waitcnt lgkmcnt(0)
	v_ashrrev_i32_e32 v49, 31, v48
	v_lshlrev_b64 v[50:51], 11, v[48:49]
	v_lshl_add_u64 v[58:59], v[50:51], 0, v[144:145]
	v_lshl_add_u64 v[60:61], v[58:59], 2, s[52:53]
	s_waitcnt vmcnt(11)
	s_nop 1
	v_mov_b32_e32 v50, v188
	v_mov_b32_e32 v51, v189
	v_mov_b32_e32 v52, v190
	v_mov_b32_e32 v53, v191
	s_waitcnt vmcnt(10)
	s_nop 1
	v_mov_b32_e32 v54, v192
	v_mov_b32_e32 v55, v193
	v_mov_b32_e32 v56, v194
	v_mov_b32_e32 v57, v195
	v_lshlrev_b64 v[58:59], 1, v[58:59]
	v_lshl_add_u64 v[62:63], s[16:17], 0, v[58:59]
	v_or_b32_e32 v58, 0x100, v58
	v_pk_fma_f32 v[52:53], v[46:47], 0.5, v[52:53] op_sel_hi:[1,0,1]
	v_pk_fma_f32 v[50:51], v[44:45], 0.5, v[50:51] op_sel_hi:[1,0,1]
	v_pk_fma_f32 v[56:57], v[42:43], 0.5, v[56:57] op_sel_hi:[1,0,1]
	v_pk_fma_f32 v[54:55], v[40:41], 0.5, v[54:55] op_sel_hi:[1,0,1]
	v_cvt_pk_bf16_f32 v40, v50, v51
	v_cvt_pk_bf16_f32 v41, v52, v53
	v_mul_f32_e32 v51, v51, v51
	v_cvt_pk_bf16_f32 v42, v54, v55
	v_cvt_pk_bf16_f32 v43, v56, v57
	global_store_dwordx4 v[62:63], v[40:43], off
	s_waitcnt vmcnt(9)
	s_nop 1
	v_mov_b32_e32 v40, v196
	v_mov_b32_e32 v41, v197
	v_mov_b32_e32 v42, v198
	v_mov_b32_e32 v43, v199
	s_nop 0
	s_waitcnt vmcnt(8)
	s_nop 1
	v_mov_b32_e32 v44, v200
	v_mov_b32_e32 v45, v201
	v_mov_b32_e32 v46, v202
	v_mov_b32_e32 v47, v203
	v_mul_f32_e32 v53, v53, v53
	v_mul_f32_e32 v55, v55, v55
	v_fmac_f32_e32 v51, v50, v50
	v_fmac_f32_e32 v53, v52, v52
	v_mul_f32_e32 v57, v57, v57
	v_fmac_f32_e32 v55, v54, v54
	v_add_f32_e32 v50, v51, v53
	v_fmac_f32_e32 v57, v56, v56
	v_add_f32_e32 v50, v55, v50
	v_add_f32_e32 v50, v57, v50
	v_pk_fma_f32 v[38:39], v[38:39], 0.5, v[42:43] op_sel_hi:[1,0,1]
	v_pk_fma_f32 v[36:37], v[36:37], 0.5, v[40:41] op_sel_hi:[1,0,1]
	v_pk_fma_f32 v[40:41], v[34:35], 0.5, v[46:47] op_sel_hi:[1,0,1]
	v_pk_fma_f32 v[32:33], v[32:33], 0.5, v[44:45] op_sel_hi:[1,0,1]
	v_mul_f32_e32 v34, v37, v37
	v_mul_f32_e32 v35, v39, v39
	v_mul_f32_e32 v42, v33, v33
	v_fmac_f32_e32 v34, v36, v36
	v_fmac_f32_e32 v35, v38, v38
	v_mul_f32_e32 v43, v41, v41
	v_fmac_f32_e32 v42, v32, v32
	v_add_f32_e32 v34, v34, v35
	v_add_f32_e32 v34, v42, v34
	v_fmac_f32_e32 v43, v40, v40
	v_add_f32_e32 v34, v43, v34
	v_add_f32_e32 v42, v50, v34
	ds_bpermute_b32 v43, v120, v42
	v_cvt_pk_bf16_f32 v34, v36, v37
	v_cvt_pk_bf16_f32 v35, v38, v39
	v_cvt_pk_bf16_f32 v36, v32, v33
	v_lshl_add_u64 v[38:39], s[16:17], 0, v[58:59]
	s_waitcnt lgkmcnt(0)
	v_add_f32_e32 v32, v42, v43
	ds_bpermute_b32 v33, v114, v32
	v_cvt_pk_bf16_f32 v37, v40, v41
	global_store_dwordx4 v[38:39], v[34:37], off
	s_and_saveexec_b64 s[46:47], s[2:3]
	s_cbranch_execz .LBB0_274
	v_lshl_add_u64 v[34:35], v[48:49], 2, s[18:19]
	s_waitcnt lgkmcnt(0)
	v_add_f32_e32 v32, v32, v33
	global_atomic_add_f32 v[34:35], v32, off
; __device__ __forceinline__ unsigned cvt_pk_bf16(float lo, float hi) { unsigned r; asm volatile("v_cvt_pk_bf16_f32 %0, %1, %2" : "=v"(r) : "v"(lo), "v"(hi)); return r; }
;     __device__ __forceinline__ void operator()(const f32x4 (&acc)[2][2][4][2], const Unit& u, int wr, int wc, int fr, int fq) const {
;         const int row0 = u.pm * BM + wr * 64 + fr; const int col0 = u.pn * BM + wc * 32 + 8 * fq;
; #pragma unroll
;         for (int ai = 0; ai < 2; ++ai)
; #pragma unroll
;             for (int m = 0; m < 4; ++m) { const int row = row0 + ai * HALF + m * 16; const size_t off = (size_t)row * ldc + col0; float part = 0.f;
; #pragma unroll
;                 for (int bj = 0; bj < 2; ++bj) { const size_t idx = off + bj * HALF;
;                     f32x4 b0, b1;
;                     if constexpr (BASE_BF16) { const u32x4 r = *(const u32x4*)(baseb + idx);
;                         b0 = (f32x4){__builtin_bit_cast(float, r.x << 16), __builtin_bit_cast(float, r.x & 0xffff0000u), __builtin_bit_cast(float, r.y << 16), __builtin_bit_cast(float, r.y & 0xffff0000u)};
;                         b1 = (f32x4){__builtin_bit_cast(float, r.z << 16), __builtin_bit_cast(float, r.z & 0xffff0000u), __builtin_bit_cast(float, r.w << 16), __builtin_bit_cast(float, r.w & 0xffff0000u)}; }
;                     else { b0 = *(const f32x4*)(base + idx); b1 = *(const f32x4*)(base + idx + 4); }
;                     const f32x4 o0 = b0 + acc[ai][bj][m][0] * alpha, o1 = b1 + acc[ai][bj][m][1] * alpha;
;                     if constexpr (WRITE_F32) { *(f32x4*)(out + idx) = o0; *(f32x4*)(out + idx + 4) = o1; }
;                     if constexpr (WRITE_XB) {
;                         part += (o0[0] * o0[0] + o0[1] * o0[1]) + (o0[2] * o0[2] + o0[3] * o0[3]) + (o1[0] * o1[0] + o1[1] * o1[1]) + (o1[2] * o1[2] + o1[3] * o1[3]);
;                         u32x4 w; w.x = cvt_pk_bf16(o0[0], o0[1]); w.y = cvt_pk_bf16(o0[2], o0[3]); w.z = cvt_pk_bf16(o1[0], o1[1]); w.w = cvt_pk_bf16(o1[2], o1[3]);
;                         *(u32x4*)(xb + idx) = w; } }
;                 if constexpr (WRITE_XB) { part += __shfl_xor(part, 16); part += __shfl_xor(part, 32);
;                     if (fq == 0) atomicAdd(ss + row, part); } }
;     }
.LBB0_274:
	s_or_b64 exec, exec, s[46:47]
	v_add_u32_e32 v32, 0xa0, v146
	s_waitcnt lgkmcnt(0)
	v_ashrrev_i32_e32 v33, 31, v32
	v_lshlrev_b64 v[34:35], 11, v[32:33]
	v_lshl_add_u64 v[42:43], v[34:35], 0, v[144:145]
	v_lshl_add_u64 v[44:45], v[42:43], 2, s[52:53]
	s_waitcnt vmcnt(7)
	s_nop 1
	v_mov_b32_e32 v34, v204
	v_mov_b32_e32 v35, v205
	v_mov_b32_e32 v36, v206
	v_mov_b32_e32 v37, v207
	s_waitcnt vmcnt(6)
	s_nop 1
	v_mov_b32_e32 v38, v208
	v_mov_b32_e32 v39, v209
	v_mov_b32_e32 v40, v210
	v_mov_b32_e32 v41, v211
	v_lshlrev_b64 v[42:43], 1, v[42:43]
	v_lshl_add_u64 v[46:47], s[16:17], 0, v[42:43]
	v_or_b32_e32 v42, 0x100, v42
	v_pk_fma_f32 v[36:37], v[30:31], 0.5, v[36:37] op_sel_hi:[1,0,1]
	v_pk_fma_f32 v[34:35], v[28:29], 0.5, v[34:35] op_sel_hi:[1,0,1]
	v_pk_fma_f32 v[40:41], v[26:27], 0.5, v[40:41] op_sel_hi:[1,0,1]
	v_pk_fma_f32 v[38:39], v[24:25], 0.5, v[38:39] op_sel_hi:[1,0,1]
	v_cvt_pk_bf16_f32 v24, v34, v35
	v_cvt_pk_bf16_f32 v25, v36, v37
	v_mul_f32_e32 v35, v35, v35
	v_cvt_pk_bf16_f32 v26, v38, v39
	v_cvt_pk_bf16_f32 v27, v40, v41
	global_store_dwordx4 v[46:47], v[24:27], off
	s_waitcnt vmcnt(5)
	s_nop 1
	v_mov_b32_e32 v24, v212
	v_mov_b32_e32 v25, v213
	v_mov_b32_e32 v26, v214
	v_mov_b32_e32 v27, v215
	s_nop 0
	s_waitcnt vmcnt(4)
	s_nop 1
	v_mov_b32_e32 v28, v220
	v_mov_b32_e32 v29, v221
	v_mov_b32_e32 v30, v222
	v_mov_b32_e32 v31, v223
	v_mul_f32_e32 v37, v37, v37
	v_mul_f32_e32 v39, v39, v39
	v_fmac_f32_e32 v35, v34, v34
	v_fmac_f32_e32 v37, v36, v36
	v_mul_f32_e32 v41, v41, v41
	v_fmac_f32_e32 v39, v38, v38
	v_add_f32_e32 v34, v35, v37
	v_fmac_f32_e32 v41, v40, v40
	v_add_f32_e32 v34, v39, v34
	v_add_f32_e32 v34, v41, v34
	v_pk_fma_f32 v[22:23], v[22:23], 0.5, v[26:27] op_sel_hi:[1,0,1]
	v_pk_fma_f32 v[20:21], v[20:21], 0.5, v[24:25] op_sel_hi:[1,0,1]
	v_pk_fma_f32 v[24:25], v[18:19], 0.5, v[30:31] op_sel_hi:[1,0,1]
	v_pk_fma_f32 v[16:17], v[16:17], 0.5, v[28:29] op_sel_hi:[1,0,1]
	v_mul_f32_e32 v18, v21, v21
	v_mul_f32_e32 v19, v23, v23
	v_mul_f32_e32 v26, v17, v17
	v_fmac_f32_e32 v18, v20, v20
	v_fmac_f32_e32 v19, v22, v22
	v_mul_f32_e32 v27, v25, v25
	v_fmac_f32_e32 v26, v16, v16
	v_add_f32_e32 v18, v18, v19
	v_add_f32_e32 v18, v26, v18
	v_fmac_f32_e32 v27, v24, v24
	v_add_f32_e32 v18, v27, v18
	v_add_f32_e32 v26, v34, v18
	ds_bpermute_b32 v27, v120, v26
	v_cvt_pk_bf16_f32 v18, v20, v21
	v_cvt_pk_bf16_f32 v19, v22, v23
	v_cvt_pk_bf16_f32 v20, v16, v17
	v_lshl_add_u64 v[22:23], s[16:17], 0, v[42:43]
	s_waitcnt lgkmcnt(0)
	v_add_f32_e32 v16, v26, v27
	ds_bpermute_b32 v17, v114, v16
	v_cvt_pk_bf16_f32 v21, v24, v25
	global_store_dwordx4 v[22:23], v[18:21], off
	s_and_saveexec_b64 s[46:47], s[2:3]
	s_cbranch_execz .LBB0_276
	v_lshl_add_u64 v[18:19], v[32:33], 2, s[18:19]
	s_waitcnt lgkmcnt(0)
	v_add_f32_e32 v16, v16, v17
	global_atomic_add_f32 v[18:19], v16, off
.LBB0_276:
	s_or_b64 exec, exec, s[46:47]
	v_add_u32_e32 v16, 0xb0, v146
	s_waitcnt lgkmcnt(0)
	v_ashrrev_i32_e32 v17, 31, v16
	v_lshlrev_b64 v[18:19], 11, v[16:17]
	v_lshl_add_u64 v[26:27], v[18:19], 0, v[144:145]
	v_lshl_add_u64 v[28:29], v[26:27], 2, s[52:53]
	s_waitcnt vmcnt(3)
	s_nop 1
	v_mov_b32_e32 v18, v224
	v_mov_b32_e32 v19, v225
	v_mov_b32_e32 v20, v226
	v_mov_b32_e32 v21, v227
	s_waitcnt vmcnt(2)
	s_nop 1
	v_mov_b32_e32 v22, v228
	v_mov_b32_e32 v23, v229
	v_mov_b32_e32 v24, v230
	v_mov_b32_e32 v25, v231
	v_lshlrev_b64 v[26:27], 1, v[26:27]
	v_lshl_add_u64 v[30:31], s[16:17], 0, v[26:27]
	v_or_b32_e32 v26, 0x100, v26
	v_pk_fma_f32 v[20:21], v[14:15], 0.5, v[20:21] op_sel_hi:[1,0,1]
	v_pk_fma_f32 v[18:19], v[12:13], 0.5, v[18:19] op_sel_hi:[1,0,1]
	v_pk_fma_f32 v[24:25], v[10:11], 0.5, v[24:25] op_sel_hi:[1,0,1]
	v_pk_fma_f32 v[22:23], v[8:9], 0.5, v[22:23] op_sel_hi:[1,0,1]
	v_cvt_pk_bf16_f32 v8, v18, v19
	v_cvt_pk_bf16_f32 v9, v20, v21
	v_mul_f32_e32 v19, v19, v19
	v_cvt_pk_bf16_f32 v10, v22, v23
	v_cvt_pk_bf16_f32 v11, v24, v25
	global_store_dwordx4 v[30:31], v[8:11], off
	s_waitcnt vmcnt(1)
	s_nop 1
	v_mov_b32_e32 v8, v232
	v_mov_b32_e32 v9, v233
	v_mov_b32_e32 v10, v234
	v_mov_b32_e32 v11, v235
	s_nop 0
	s_waitcnt vmcnt(0)
	s_nop 1
	v_mov_b32_e32 v12, v236
	v_mov_b32_e32 v13, v237
	v_mov_b32_e32 v14, v238
	v_mov_b32_e32 v15, v239
	v_mul_f32_e32 v21, v21, v21
	v_mul_f32_e32 v23, v23, v23
	v_fmac_f32_e32 v19, v18, v18
	v_fmac_f32_e32 v21, v20, v20
	v_mul_f32_e32 v25, v25, v25
	v_fmac_f32_e32 v23, v22, v22
	v_add_f32_e32 v18, v19, v21
	v_fmac_f32_e32 v25, v24, v24
	v_add_f32_e32 v18, v23, v18
	v_add_f32_e32 v18, v25, v18
	v_pk_fma_f32 v[6:7], v[6:7], 0.5, v[10:11] op_sel_hi:[1,0,1]
	v_pk_fma_f32 v[4:5], v[4:5], 0.5, v[8:9] op_sel_hi:[1,0,1]
	v_pk_fma_f32 v[8:9], v[2:3], 0.5, v[14:15] op_sel_hi:[1,0,1]
	v_pk_fma_f32 v[0:1], v[0:1], 0.5, v[12:13] op_sel_hi:[1,0,1]
	v_mul_f32_e32 v2, v5, v5
	v_mul_f32_e32 v3, v7, v7
	v_mul_f32_e32 v10, v1, v1
	v_fmac_f32_e32 v2, v4, v4
	v_fmac_f32_e32 v3, v6, v6
	v_mul_f32_e32 v11, v9, v9
	v_fmac_f32_e32 v10, v0, v0
	v_add_f32_e32 v2, v2, v3
	v_add_f32_e32 v2, v10, v2
	v_fmac_f32_e32 v11, v8, v8
	v_add_f32_e32 v2, v11, v2
	v_add_f32_e32 v10, v18, v2
	ds_bpermute_b32 v11, v120, v10
	v_cvt_pk_bf16_f32 v2, v4, v5
	v_cvt_pk_bf16_f32 v3, v6, v7
	v_cvt_pk_bf16_f32 v4, v0, v1
	v_lshl_add_u64 v[6:7], s[16:17], 0, v[26:27]
	s_waitcnt lgkmcnt(0)
	v_add_f32_e32 v0, v10, v11
	ds_bpermute_b32 v1, v114, v0
	v_cvt_pk_bf16_f32 v5, v8, v9
	global_store_dwordx4 v[6:7], v[2:5], off
	s_and_saveexec_b64 s[46:47], s[2:3]
	s_cbranch_execz .LBB0_278
	v_lshl_add_u64 v[2:3], v[16:17], 2, s[18:19]
	s_waitcnt lgkmcnt(0)
	v_add_f32_e32 v0, v0, v1
	global_atomic_add_f32 v[2:3], v0, off

; __device__ __forceinline__ unsigned cvt_pk_bf16(float lo, float hi) { unsigned r; asm volatile("v_cvt_pk_bf16_f32 %0, %1, %2" : "=v"(r) : "v"(lo), "v"(hi)); return r; }
;     __device__ __forceinline__ void operator()(const f32x4 (&acc)[2][2][4][2], const Unit& u, int wr, int wc, int fr, int fq) const {
;         const int row0 = u.pm * BM + wr * 64 + fr; const int col0 = u.pn * BM + wc * 32 + 8 * fq;
; #pragma unroll
;         for (int ai = 0; ai < 2; ++ai)
; #pragma unroll
;             for (int m = 0; m < 4; ++m) { const int row = row0 + ai * HALF + m * 16; const size_t off = (size_t)row * ldc + col0; float part = 0.f;
; #pragma unroll
;                 for (int bj = 0; bj < 2; ++bj) { const size_t idx = off + bj * HALF;
;                     f32x4 b0, b1;
;                     if constexpr (BASE_BF16) { const u32x4 r = *(const u32x4*)(baseb + idx);
;                         b0 = (f32x4){__builtin_bit_cast(float, r.x << 16), __builtin_bit_cast(float, r.x & 0xffff0000u), __builtin_bit_cast(float, r.y << 16), __builtin_bit_cast(float, r.y & 0xffff0000u)};
;                         b1 = (f32x4){__builtin_bit_cast(float, r.z << 16), __builtin_bit_cast(float, r.z & 0xffff0000u), __builtin_bit_cast(float, r.w << 16), __builtin_bit_cast(float, r.w & 0xffff0000u)}; }
;                     else { b0 = *(const f32x4*)(base + idx); b1 = *(const f32x4*)(base + idx + 4); }
;                     const f32x4 o0 = b0 + acc[ai][bj][m][0] * alpha, o1 = b1 + acc[ai][bj][m][1] * alpha;
;                     if constexpr (WRITE_F32) { *(f32x4*)(out + idx) = o0; *(f32x4*)(out + idx + 4) = o1; }
;                     if constexpr (WRITE_XB) {
;                         part += (o0[0] * o0[0] + o0[1] * o0[1]) + (o0[2] * o0[2] + o0[3] * o0[3]) + (o1[0] * o1[0] + o1[1] * o1[1]) + (o1[2] * o1[2] + o1[3] * o1[3]);
;                         u32x4 w; w.x = cvt_pk_bf16(o0[0], o0[1]); w.y = cvt_pk_bf16(o0[2], o0[3]); w.z = cvt_pk_bf16(o1[0], o1[1]); w.w = cvt_pk_bf16(o1[2], o1[3]);
;                         *(u32x4*)(xb + idx) = w; } }
;                 if constexpr (WRITE_XB) { part += __shfl_xor(part, 16); part += __shfl_xor(part, 32);
;                     if (fq == 0) atomicAdd(ss + row, part); } }
;     }
.LBB0_687:
	v_lshl_add_u32 v146, s42, 8, v148
	v_lshl_or_b32 v144, s44, 8, v150
	v_ashrrev_i32_e32 v147, 31, v146
	v_ashrrev_i32_e32 v145, 31, v144
	v_mov_b32_e32 v248, v146
	v_lshl_add_u32 v248, v248, 11, v144
	v_lshlrev_b32_e32 v248, 1, v248
	global_load_dwordx4 v[172:175], v248, s[14:15]
	global_load_dwordx4 v[176:179], v248, s[14:15] offset:256
	v_add_u32_e32 v249, 16, v146
	v_lshl_add_u32 v249, v249, 11, v144
	v_lshlrev_b32_e32 v249, 1, v249
	global_load_dwordx4 v[180:183], v249, s[14:15]
	global_load_dwordx4 v[184:187], v249, s[14:15] offset:256
	v_add_u32_e32 v250, 32, v146
	v_lshl_add_u32 v250, v250, 11, v144
	v_lshlrev_b32_e32 v250, 1, v250
	global_load_dwordx4 v[188:191], v250, s[14:15]
	global_load_dwordx4 v[192:195], v250, s[14:15] offset:256
	v_add_u32_e32 v251, 48, v146
	v_lshl_add_u32 v251, v251, 11, v144
	v_lshlrev_b32_e32 v251, 1, v251
	global_load_dwordx4 v[196:199], v251, s[14:15]
	global_load_dwordx4 v[200:203], v251, s[14:15] offset:256
	v_add_u32_e32 v252, 0x80, v146
	v_lshl_add_u32 v252, v252, 11, v144
	v_lshlrev_b32_e32 v252, 1, v252
	global_load_dwordx4 v[204:207], v252, s[14:15]
	global_load_dwordx4 v[208:211], v252, s[14:15] offset:256
	v_add_u32_e32 v253, 0x90, v146
	v_lshl_add_u32 v253, v253, 11, v144
	v_lshlrev_b32_e32 v253, 1, v253
	global_load_dwordx4 v[212:215], v253, s[14:15]
	global_load_dwordx4 v[220:223], v253, s[14:15] offset:256
	v_add_u32_e32 v254, 0xa0, v146
	v_lshl_add_u32 v254, v254, 11, v144
	v_lshlrev_b32_e32 v254, 1, v254
	global_load_dwordx4 v[224:227], v254, s[14:15]
	global_load_dwordx4 v[228:231], v254, s[14:15] offset:256
	v_add_u32_e32 v255, 0xb0, v146
	v_lshl_add_u32 v255, v255, 11, v144
	v_lshlrev_b32_e32 v255, 1, v255
	global_load_dwordx4 v[232:235], v255, s[14:15]
	global_load_dwordx4 v[236:239], v255, s[14:15] offset:256
	v_lshlrev_b64 v[156:157], 11, v[146:147]
	v_lshl_add_u64 v[156:157], v[156:157], 0, v[144:145]
	v_lshlrev_b64 v[160:161], 1, v[156:157]
	v_lshl_add_u64 v[156:157], s[14:15], 0, v[160:161]
	s_waitcnt vmcnt(15)
	s_nop 1
	v_mov_b32_e32 v156, v172
	v_mov_b32_e32 v157, v173
	v_mov_b32_e32 v158, v174
	v_mov_b32_e32 v159, v175
	v_lshl_add_u64 v[162:163], s[16:17], 0, v[160:161]
	v_or_b32_e32 v160, 0x100, v160
	v_lshl_add_u64 v[164:165], s[14:15], 0, v[160:161]
	v_xor_b32_e32 v155, 32, v154
	v_lshlrev_b32_e32 v166, 16, v156
	v_and_b32_e32 v167, 0xffff0000, v156
	v_lshlrev_b32_e32 v156, 16, v157
	v_and_b32_e32 v157, 0xffff0000, v157
	v_lshlrev_b32_e32 v168, 16, v158
	v_and_b32_e32 v169, 0xffff0000, v158
	v_lshlrev_b32_e32 v158, 16, v159
	v_and_b32_e32 v159, 0xffff0000, v159
	v_pk_add_f32 v[126:127], v[126:127], v[156:157]
	v_pk_add_f32 v[166:167], v[124:125], v[166:167]
	v_pk_add_f32 v[170:171], v[122:123], v[158:159]
	v_pk_add_f32 v[168:169], v[120:121], v[168:169]
	v_cvt_pk_bf16_f32 v122, v166, v167
	v_cvt_pk_bf16_f32 v123, v126, v127
	v_mul_f32_e32 v127, v127, v127
	v_cvt_pk_bf16_f32 v124, v168, v169
	v_cvt_pk_bf16_f32 v125, v170, v171
	s_waitcnt vmcnt(14)
	s_nop 1
	v_mov_b32_e32 v156, v176
	v_mov_b32_e32 v157, v177
	v_mov_b32_e32 v158, v178
	v_mov_b32_e32 v159, v179
	v_mul_f32_e32 v164, v167, v167
	v_mul_f32_e32 v165, v169, v169
	v_fmac_f32_e32 v164, v166, v166
	v_fmac_f32_e32 v127, v126, v126
	v_mul_f32_e32 v167, v171, v171
	v_fmac_f32_e32 v165, v168, v168
	v_add_f32_e32 v126, v164, v127
	v_fmac_f32_e32 v167, v170, v170
	v_add_f32_e32 v126, v165, v126
	v_add_f32_e32 v166, v167, v126
	v_and_b32_e32 v121, 64, v154
	v_xor_b32_e32 v120, 16, v154
	v_add_u32_e32 v121, 64, v121
	v_cmp_lt_i32_e32 vcc, v120, v121
	global_store_dwordx4 v[162:163], v[122:125], off
	v_lshlrev_b32_e32 v126, 16, v156
	v_and_b32_e32 v127, 0xffff0000, v156
	v_lshlrev_b32_e32 v156, 16, v157
	v_and_b32_e32 v157, 0xffff0000, v157
	v_lshlrev_b32_e32 v164, 16, v158
	v_and_b32_e32 v165, 0xffff0000, v158
	v_pk_add_f32 v[118:119], v[118:119], v[156:157]
	v_pk_add_f32 v[116:117], v[116:117], v[126:127]
	v_lshlrev_b32_e32 v158, 16, v159
	v_and_b32_e32 v159, 0xffff0000, v159
	v_pk_add_f32 v[156:157], v[112:113], v[164:165]
	v_mul_f32_e32 v112, v117, v117
	v_mul_f32_e32 v113, v119, v119
	v_pk_add_f32 v[126:127], v[114:115], v[158:159]
	v_mul_f32_e32 v114, v157, v157
	v_fmac_f32_e32 v112, v116, v116
	v_fmac_f32_e32 v113, v118, v118
	v_mul_f32_e32 v115, v127, v127
	v_fmac_f32_e32 v114, v156, v156
	v_add_f32_e32 v112, v112, v113
	v_fmac_f32_e32 v115, v126, v126
	v_add_f32_e32 v112, v114, v112
	v_cndmask_b32_e32 v120, v154, v120, vcc
	v_add_f32_e32 v112, v115, v112
	v_lshlrev_b32_e32 v120, 2, v120
	v_add_f32_e32 v112, v166, v112
	ds_bpermute_b32 v113, v120, v112
	v_cmp_lt_i32_e32 vcc, v155, v121
	v_lshl_add_u64 v[122:123], s[16:17], 0, v[160:161]
	v_cvt_pk_bf16_f32 v116, v116, v117
	v_cvt_pk_bf16_f32 v117, v118, v119
	s_waitcnt lgkmcnt(0)
	v_add_f32_e32 v112, v112, v113
	v_cndmask_b32_e32 v114, v154, v155, vcc
	v_lshlrev_b32_e32 v114, 2, v114
	ds_bpermute_b32 v113, v114, v112
	v_cvt_pk_bf16_f32 v118, v156, v157
	v_cvt_pk_bf16_f32 v119, v126, v127
	global_store_dwordx4 v[122:123], v[116:119], off
	s_and_saveexec_b64 s[42:43], s[2:3]
	s_cbranch_execz .LBB0_689
	v_lshl_add_u64 v[116:117], v[146:147], 2, s[18:19]
	s_waitcnt lgkmcnt(0)
	v_add_f32_e32 v112, v112, v113
	global_atomic_add_f32 v[116:117], v112, off
; __device__ __forceinline__ unsigned cvt_pk_bf16(float lo, float hi) { unsigned r; asm volatile("v_cvt_pk_bf16_f32 %0, %1, %2" : "=v"(r) : "v"(lo), "v"(hi)); return r; }
;     __device__ __forceinline__ void operator()(const f32x4 (&acc)[2][2][4][2], const Unit& u, int wr, int wc, int fr, int fq) const {
;         const int row0 = u.pm * BM + wr * 64 + fr; const int col0 = u.pn * BM + wc * 32 + 8 * fq;
; #pragma unroll
;         for (int ai = 0; ai < 2; ++ai)
; #pragma unroll
;             for (int m = 0; m < 4; ++m) { const int row = row0 + ai * HALF + m * 16; const size_t off = (size_t)row * ldc + col0; float part = 0.f;
; #pragma unroll
;                 for (int bj = 0; bj < 2; ++bj) { const size_t idx = off + bj * HALF;
;                     f32x4 b0, b1;
;                     if constexpr (BASE_BF16) { const u32x4 r = *(const u32x4*)(baseb + idx);
;                         b0 = (f32x4){__builtin_bit_cast(float, r.x << 16), __builtin_bit_cast(float, r.x & 0xffff0000u), __builtin_bit_cast(float, r.y << 16), __builtin_bit_cast(float, r.y & 0xffff0000u)};
;                         b1 = (f32x4){__builtin_bit_cast(float, r.z << 16), __builtin_bit_cast(float, r.z & 0xffff0000u), __builtin_bit_cast(float, r.w << 16), __builtin_bit_cast(float, r.w & 0xffff0000u)}; }
;                     else { b0 = *(const f32x4*)(base + idx); b1 = *(const f32x4*)(base + idx + 4); }
;                     const f32x4 o0 = b0 + acc[ai][bj][m][0] * alpha, o1 = b1 + acc[ai][bj][m][1] * alpha;
;                     if constexpr (WRITE_F32) { *(f32x4*)(out + idx) = o0; *(f32x4*)(out + idx + 4) = o1; }
;                     if constexpr (WRITE_XB) {
;                         part += (o0[0] * o0[0] + o0[1] * o0[1]) + (o0[2] * o0[2] + o0[3] * o0[3]) + (o1[0] * o1[0] + o1[1] * o1[1]) + (o1[2] * o1[2] + o1[3] * o1[3]);
;                         u32x4 w; w.x = cvt_pk_bf16(o0[0], o0[1]); w.y = cvt_pk_bf16(o0[2], o0[3]); w.z = cvt_pk_bf16(o1[0], o1[1]); w.w = cvt_pk_bf16(o1[2], o1[3]);
;                         *(u32x4*)(xb + idx) = w; } }
;                 if constexpr (WRITE_XB) { part += __shfl_xor(part, 16); part += __shfl_xor(part, 32);
;                     if (fq == 0) atomicAdd(ss + row, part); } }
;     }
.LBB0_689:
	s_or_b64 exec, exec, s[42:43]
	v_or_b32_e32 v112, 16, v146
	s_waitcnt lgkmcnt(0)
	v_ashrrev_i32_e32 v113, 31, v112
	v_lshlrev_b64 v[116:117], 11, v[112:113]
	v_lshl_add_u64 v[116:117], v[116:117], 0, v[144:145]
	v_lshlrev_b64 v[122:123], 1, v[116:117]
	v_lshl_add_u64 v[116:117], s[14:15], 0, v[122:123]
	s_waitcnt vmcnt(13)
	s_nop 1
	v_mov_b32_e32 v116, v180
	v_mov_b32_e32 v117, v181
	v_mov_b32_e32 v118, v182
	v_mov_b32_e32 v119, v183
	v_lshl_add_u64 v[124:125], s[16:17], 0, v[122:123]
	v_or_b32_e32 v122, 0x100, v122
	v_lshl_add_u64 v[126:127], s[14:15], 0, v[122:123]
	v_lshlrev_b32_e32 v156, 16, v116
	v_and_b32_e32 v157, 0xffff0000, v116
	v_lshlrev_b32_e32 v116, 16, v117
	v_and_b32_e32 v117, 0xffff0000, v117
	v_lshlrev_b32_e32 v158, 16, v118
	v_and_b32_e32 v159, 0xffff0000, v118
	v_lshlrev_b32_e32 v118, 16, v119
	v_and_b32_e32 v119, 0xffff0000, v119
	v_pk_add_f32 v[116:117], v[110:111], v[116:117]
	v_pk_add_f32 v[156:157], v[108:109], v[156:157]
	v_pk_add_f32 v[118:119], v[106:107], v[118:119]
	v_pk_add_f32 v[158:159], v[104:105], v[158:159]
	v_cvt_pk_bf16_f32 v104, v156, v157
	v_cvt_pk_bf16_f32 v105, v116, v117
	v_mul_f32_e32 v115, v157, v157
	v_cvt_pk_bf16_f32 v106, v158, v159
	v_cvt_pk_bf16_f32 v107, v118, v119
	s_waitcnt vmcnt(12)
	s_nop 1
	v_mov_b32_e32 v108, v184
	v_mov_b32_e32 v109, v185
	v_mov_b32_e32 v110, v186
	v_mov_b32_e32 v111, v187
	v_mul_f32_e32 v117, v117, v117
	v_mul_f32_e32 v121, v159, v159
	v_fmac_f32_e32 v115, v156, v156
	v_fmac_f32_e32 v117, v116, v116
	v_mul_f32_e32 v119, v119, v119
	v_fmac_f32_e32 v121, v158, v158
	v_add_f32_e32 v115, v115, v117
	v_fmac_f32_e32 v119, v118, v118
	v_add_f32_e32 v115, v121, v115
	v_add_f32_e32 v115, v119, v115
	global_store_dwordx4 v[124:125], v[104:107], off
	v_lshlrev_b32_e32 v116, 16, v108
	v_and_b32_e32 v117, 0xffff0000, v108
	v_lshlrev_b32_e32 v108, 16, v109
	v_and_b32_e32 v109, 0xffff0000, v109
	v_lshlrev_b32_e32 v118, 16, v110
	v_and_b32_e32 v119, 0xffff0000, v110
	v_lshlrev_b32_e32 v110, 16, v111
	v_and_b32_e32 v111, 0xffff0000, v111
	v_pk_add_f32 v[102:103], v[102:103], v[108:109]
	v_pk_add_f32 v[100:101], v[100:101], v[116:117]
	v_pk_add_f32 v[108:109], v[98:99], v[110:111]
	v_pk_add_f32 v[110:111], v[96:97], v[118:119]
	v_mul_f32_e32 v96, v101, v101
	v_mul_f32_e32 v97, v103, v103
	v_mul_f32_e32 v98, v111, v111
	v_fmac_f32_e32 v96, v100, v100
	v_fmac_f32_e32 v97, v102, v102
	v_mul_f32_e32 v99, v109, v109
	v_fmac_f32_e32 v98, v110, v110
	v_add_f32_e32 v96, v96, v97
	v_add_f32_e32 v96, v98, v96
	v_fmac_f32_e32 v99, v108, v108
	v_add_f32_e32 v96, v99, v96
	v_add_f32_e32 v96, v115, v96
	ds_bpermute_b32 v97, v120, v96
	v_cvt_pk_bf16_f32 v98, v100, v101
	v_cvt_pk_bf16_f32 v99, v102, v103
	v_lshl_add_u64 v[102:103], s[16:17], 0, v[122:123]
	v_cvt_pk_bf16_f32 v100, v110, v111
	s_waitcnt lgkmcnt(0)
	v_add_f32_e32 v96, v96, v97
	ds_bpermute_b32 v97, v114, v96
	v_cvt_pk_bf16_f32 v101, v108, v109
	global_store_dwordx4 v[102:103], v[98:101], off
	s_and_saveexec_b64 s[42:43], s[2:3]
	s_cbranch_execz .LBB0_691
	v_lshl_add_u64 v[98:99], v[112:113], 2, s[18:19]
	s_waitcnt lgkmcnt(0)
	v_add_f32_e32 v96, v96, v97
	global_atomic_add_f32 v[98:99], v96, off
.LBB0_691:
	s_or_b64 exec, exec, s[42:43]
	v_or_b32_e32 v96, 32, v146
	s_waitcnt lgkmcnt(0)
	v_ashrrev_i32_e32 v97, 31, v96
	v_lshlrev_b64 v[98:99], 11, v[96:97]
	v_lshl_add_u64 v[98:99], v[98:99], 0, v[144:145]
	v_lshlrev_b64 v[102:103], 1, v[98:99]
	v_lshl_add_u64 v[98:99], s[14:15], 0, v[102:103]
	s_waitcnt vmcnt(11)
	s_nop 1
	v_mov_b32_e32 v98, v188
	v_mov_b32_e32 v99, v189
	v_mov_b32_e32 v100, v190
	v_mov_b32_e32 v101, v191
	v_lshl_add_u64 v[104:105], s[16:17], 0, v[102:103]
	v_or_b32_e32 v102, 0x100, v102
	v_lshl_add_u64 v[106:107], s[14:15], 0, v[102:103]
	v_lshlrev_b32_e32 v108, 16, v98
	v_and_b32_e32 v109, 0xffff0000, v98
	v_lshlrev_b32_e32 v98, 16, v99
	v_and_b32_e32 v99, 0xffff0000, v99
	v_lshlrev_b32_e32 v110, 16, v100
	v_and_b32_e32 v111, 0xffff0000, v100
	v_lshlrev_b32_e32 v100, 16, v101
	v_and_b32_e32 v101, 0xffff0000, v101
	v_pk_add_f32 v[98:99], v[94:95], v[98:99]
	v_pk_add_f32 v[108:109], v[92:93], v[108:109]
	v_pk_add_f32 v[100:101], v[90:91], v[100:101]
	v_pk_add_f32 v[110:111], v[88:89], v[110:111]
	v_cvt_pk_bf16_f32 v88, v108, v109
	v_cvt_pk_bf16_f32 v89, v98, v99
	v_mul_f32_e32 v99, v99, v99
	v_cvt_pk_bf16_f32 v90, v110, v111
	v_cvt_pk_bf16_f32 v91, v100, v101
	s_waitcnt vmcnt(10)
	s_nop 1
	v_mov_b32_e32 v92, v192
	v_mov_b32_e32 v93, v193
	v_mov_b32_e32 v94, v194
	v_mov_b32_e32 v95, v195
	v_mul_f32_e32 v106, v109, v109
	v_mul_f32_e32 v107, v111, v111
	v_fmac_f32_e32 v106, v108, v108
	v_fmac_f32_e32 v99, v98, v98
	v_mul_f32_e32 v101, v101, v101
	v_fmac_f32_e32 v107, v110, v110
	v_add_f32_e32 v98, v106, v99
	v_fmac_f32_e32 v101, v100, v100
	v_add_f32_e32 v98, v107, v98
	v_add_f32_e32 v106, v101, v98
	global_store_dwordx4 v[104:105], v[88:91], off
	v_lshlrev_b32_e32 v98, 16, v92
	v_and_b32_e32 v99, 0xffff0000, v92
	v_lshlrev_b32_e32 v92, 16, v93
	v_and_b32_e32 v93, 0xffff0000, v93
	v_lshlrev_b32_e32 v100, 16, v94
	v_and_b32_e32 v101, 0xffff0000, v94
	v_lshlrev_b32_e32 v94, 16, v95
	v_and_b32_e32 v95, 0xffff0000, v95
	v_pk_add_f32 v[86:87], v[86:87], v[92:93]
	v_pk_add_f32 v[84:85], v[84:85], v[98:99]
	v_pk_add_f32 v[92:93], v[82:83], v[94:95]
	v_pk_add_f32 v[94:95], v[80:81], v[100:101]
	v_mul_f32_e32 v80, v85, v85
	v_mul_f32_e32 v81, v87, v87
	v_mul_f32_e32 v82, v95, v95
	v_fmac_f32_e32 v80, v84, v84
	v_fmac_f32_e32 v81, v86, v86
	v_mul_f32_e32 v83, v93, v93
	v_fmac_f32_e32 v82, v94, v94
	v_add_f32_e32 v80, v80, v81
	v_add_f32_e32 v80, v82, v80
	v_fmac_f32_e32 v83, v92, v92
	v_add_f32_e32 v80, v83, v80
	v_add_f32_e32 v80, v106, v80
	ds_bpermute_b32 v81, v120, v80
	v_cvt_pk_bf16_f32 v82, v84, v85
	v_cvt_pk_bf16_f32 v83, v86, v87
	v_lshl_add_u64 v[86:87], s[16:17], 0, v[102:103]
	v_cvt_pk_bf16_f32 v84, v94, v95
	s_waitcnt lgkmcnt(0)
	v_add_f32_e32 v80, v80, v81
	ds_bpermute_b32 v81, v114, v80
	v_cvt_pk_bf16_f32 v85, v92, v93
	global_store_dwordx4 v[86:87], v[82:85], off
	s_and_saveexec_b64 s[42:43], s[2:3]
	s_cbranch_execz .LBB0_693
	v_lshl_add_u64 v[82:83], v[96:97], 2, s[18:19]
	s_waitcnt lgkmcnt(0)
	v_add_f32_e32 v80, v80, v81
	global_atomic_add_f32 v[82:83], v80, off
; __device__ __forceinline__ unsigned cvt_pk_bf16(float lo, float hi) { unsigned r; asm volatile("v_cvt_pk_bf16_f32 %0, %1, %2" : "=v"(r) : "v"(lo), "v"(hi)); return r; }
;     __device__ __forceinline__ void operator()(const f32x4 (&acc)[2][2][4][2], const Unit& u, int wr, int wc, int fr, int fq) const {
;         const int row0 = u.pm * BM + wr * 64 + fr; const int col0 = u.pn * BM + wc * 32 + 8 * fq;
; #pragma unroll
;         for (int ai = 0; ai < 2; ++ai)
; #pragma unroll
;             for (int m = 0; m < 4; ++m) { const int row = row0 + ai * HALF + m * 16; const size_t off = (size_t)row * ldc + col0; float part = 0.f;
; #pragma unroll
;                 for (int bj = 0; bj < 2; ++bj) { const size_t idx = off + bj * HALF;
;                     f32x4 b0, b1;
;                     if constexpr (BASE_BF16) { const u32x4 r = *(const u32x4*)(baseb + idx);
;                         b0 = (f32x4){__builtin_bit_cast(float, r.x << 16), __builtin_bit_cast(float, r.x & 0xffff0000u), __builtin_bit_cast(float, r.y << 16), __builtin_bit_cast(float, r.y & 0xffff0000u)};
;                         b1 = (f32x4){__builtin_bit_cast(float, r.z << 16), __builtin_bit_cast(float, r.z & 0xffff0000u), __builtin_bit_cast(float, r.w << 16), __builtin_bit_cast(float, r.w & 0xffff0000u)}; }
;                     else { b0 = *(const f32x4*)(base + idx); b1 = *(const f32x4*)(base + idx + 4); }
;                     const f32x4 o0 = b0 + acc[ai][bj][m][0] * alpha, o1 = b1 + acc[ai][bj][m][1] * alpha;
;                     if constexpr (WRITE_F32) { *(f32x4*)(out + idx) = o0; *(f32x4*)(out + idx + 4) = o1; }
;                     if constexpr (WRITE_XB) {
;                         part += (o0[0] * o0[0] + o0[1] * o0[1]) + (o0[2] * o0[2] + o0[3] * o0[3]) + (o1[0] * o1[0] + o1[1] * o1[1]) + (o1[2] * o1[2] + o1[3] * o1[3]);
;                         u32x4 w; w.x = cvt_pk_bf16(o0[0], o0[1]); w.y = cvt_pk_bf16(o0[2], o0[3]); w.z = cvt_pk_bf16(o1[0], o1[1]); w.w = cvt_pk_bf16(o1[2], o1[3]);
;                         *(u32x4*)(xb + idx) = w; } }
;                 if constexpr (WRITE_XB) { part += __shfl_xor(part, 16); part += __shfl_xor(part, 32);
;                     if (fq == 0) atomicAdd(ss + row, part); } }
;     }
.LBB0_693:
	s_or_b64 exec, exec, s[42:43]
	v_or_b32_e32 v80, 48, v146
	s_waitcnt lgkmcnt(0)
	v_ashrrev_i32_e32 v81, 31, v80
	v_lshlrev_b64 v[82:83], 11, v[80:81]
	v_lshl_add_u64 v[82:83], v[82:83], 0, v[144:145]
	v_lshlrev_b64 v[86:87], 1, v[82:83]
	v_lshl_add_u64 v[82:83], s[14:15], 0, v[86:87]
	s_waitcnt vmcnt(9)
	s_nop 1
	v_mov_b32_e32 v82, v196
	v_mov_b32_e32 v83, v197
	v_mov_b32_e32 v84, v198
	v_mov_b32_e32 v85, v199
	v_lshl_add_u64 v[88:89], s[16:17], 0, v[86:87]
	v_or_b32_e32 v86, 0x100, v86
	v_lshl_add_u64 v[90:91], s[14:15], 0, v[86:87]
	v_lshlrev_b32_e32 v92, 16, v82
	v_and_b32_e32 v93, 0xffff0000, v82
	v_lshlrev_b32_e32 v82, 16, v83
	v_and_b32_e32 v83, 0xffff0000, v83
	v_lshlrev_b32_e32 v94, 16, v84
	v_and_b32_e32 v95, 0xffff0000, v84
	v_lshlrev_b32_e32 v84, 16, v85
	v_and_b32_e32 v85, 0xffff0000, v85
	v_pk_add_f32 v[82:83], v[78:79], v[82:83]
	v_pk_add_f32 v[92:93], v[76:77], v[92:93]
	v_pk_add_f32 v[84:85], v[74:75], v[84:85]
	v_pk_add_f32 v[94:95], v[72:73], v[94:95]
	v_cvt_pk_bf16_f32 v72, v92, v93
	v_cvt_pk_bf16_f32 v73, v82, v83
	v_mul_f32_e32 v83, v83, v83
	v_cvt_pk_bf16_f32 v74, v94, v95
	v_cvt_pk_bf16_f32 v75, v84, v85
	s_waitcnt vmcnt(8)
	s_nop 1
	v_mov_b32_e32 v76, v200
	v_mov_b32_e32 v77, v201
	v_mov_b32_e32 v78, v202
	v_mov_b32_e32 v79, v203
	v_mul_f32_e32 v90, v93, v93
	v_mul_f32_e32 v91, v95, v95
	v_fmac_f32_e32 v90, v92, v92
	v_fmac_f32_e32 v83, v82, v82
	v_mul_f32_e32 v85, v85, v85
	v_fmac_f32_e32 v91, v94, v94
	v_add_f32_e32 v82, v90, v83
	v_fmac_f32_e32 v85, v84, v84
	v_add_f32_e32 v82, v91, v82
	v_add_f32_e32 v90, v85, v82
	global_store_dwordx4 v[88:89], v[72:75], off
	v_lshlrev_b32_e32 v82, 16, v76
	v_and_b32_e32 v83, 0xffff0000, v76
	v_lshlrev_b32_e32 v76, 16, v77
	v_and_b32_e32 v77, 0xffff0000, v77
	v_lshlrev_b32_e32 v84, 16, v78
	v_and_b32_e32 v85, 0xffff0000, v78
	v_lshlrev_b32_e32 v78, 16, v79
	v_and_b32_e32 v79, 0xffff0000, v79
	v_pk_add_f32 v[70:71], v[70:71], v[76:77]
	v_pk_add_f32 v[68:69], v[68:69], v[82:83]
	v_pk_add_f32 v[76:77], v[66:67], v[78:79]
	v_pk_add_f32 v[78:79], v[64:65], v[84:85]
	v_mul_f32_e32 v64, v69, v69
	v_mul_f32_e32 v65, v71, v71
	v_mul_f32_e32 v66, v79, v79
	v_fmac_f32_e32 v64, v68, v68
	v_fmac_f32_e32 v65, v70, v70
	v_mul_f32_e32 v67, v77, v77
	v_fmac_f32_e32 v66, v78, v78
	v_add_f32_e32 v64, v64, v65
	v_add_f32_e32 v64, v66, v64
	v_fmac_f32_e32 v67, v76, v76
	v_add_f32_e32 v64, v67, v64
	v_add_f32_e32 v64, v90, v64
	ds_bpermute_b32 v65, v120, v64
	v_cvt_pk_bf16_f32 v66, v68, v69
	v_cvt_pk_bf16_f32 v67, v70, v71
	v_lshl_add_u64 v[70:71], s[16:17], 0, v[86:87]
	v_cvt_pk_bf16_f32 v68, v78, v79
	s_waitcnt lgkmcnt(0)
	v_add_f32_e32 v64, v64, v65
	ds_bpermute_b32 v65, v114, v64
	v_cvt_pk_bf16_f32 v69, v76, v77
	global_store_dwordx4 v[70:71], v[66:69], off
	s_and_saveexec_b64 s[42:43], s[2:3]
	s_cbranch_execz .LBB0_695
	v_lshl_add_u64 v[66:67], v[80:81], 2, s[18:19]
	s_waitcnt lgkmcnt(0)
	v_add_f32_e32 v64, v64, v65
	global_atomic_add_f32 v[66:67], v64, off
.LBB0_695:
	s_or_b64 exec, exec, s[42:43]
	v_add_u32_e32 v64, 0x80, v146
	s_waitcnt lgkmcnt(0)
	v_ashrrev_i32_e32 v65, 31, v64
	v_lshlrev_b64 v[66:67], 11, v[64:65]
	v_lshl_add_u64 v[66:67], v[66:67], 0, v[144:145]
	v_lshlrev_b64 v[70:71], 1, v[66:67]
	v_lshl_add_u64 v[66:67], s[14:15], 0, v[70:71]
	s_waitcnt vmcnt(7)
	s_nop 1
	v_mov_b32_e32 v66, v204
	v_mov_b32_e32 v67, v205
	v_mov_b32_e32 v68, v206
	v_mov_b32_e32 v69, v207
	v_lshl_add_u64 v[72:73], s[16:17], 0, v[70:71]
	v_or_b32_e32 v70, 0x100, v70
	v_lshl_add_u64 v[74:75], s[14:15], 0, v[70:71]
	v_lshlrev_b32_e32 v76, 16, v66
	v_and_b32_e32 v77, 0xffff0000, v66
	v_lshlrev_b32_e32 v66, 16, v67
	v_and_b32_e32 v67, 0xffff0000, v67
	v_lshlrev_b32_e32 v78, 16, v68
	v_and_b32_e32 v79, 0xffff0000, v68
	v_lshlrev_b32_e32 v68, 16, v69
	v_and_b32_e32 v69, 0xffff0000, v69
	v_pk_add_f32 v[66:67], v[62:63], v[66:67]
	v_pk_add_f32 v[76:77], v[60:61], v[76:77]
	v_pk_add_f32 v[68:69], v[58:59], v[68:69]
	v_pk_add_f32 v[78:79], v[56:57], v[78:79]
	v_cvt_pk_bf16_f32 v56, v76, v77
	v_cvt_pk_bf16_f32 v57, v66, v67
	v_mul_f32_e32 v67, v67, v67
	v_cvt_pk_bf16_f32 v58, v78, v79
	v_cvt_pk_bf16_f32 v59, v68, v69
	s_waitcnt vmcnt(6)
	s_nop 1
	v_mov_b32_e32 v60, v208
	v_mov_b32_e32 v61, v209
	v_mov_b32_e32 v62, v210
	v_mov_b32_e32 v63, v211
	v_mul_f32_e32 v74, v77, v77
	v_mul_f32_e32 v75, v79, v79
	v_fmac_f32_e32 v74, v76, v76
	v_fmac_f32_e32 v67, v66, v66
	v_mul_f32_e32 v69, v69, v69
	v_fmac_f32_e32 v75, v78, v78
	v_add_f32_e32 v66, v74, v67
	v_fmac_f32_e32 v69, v68, v68
	v_add_f32_e32 v66, v75, v66
	v_add_f32_e32 v74, v69, v66
	global_store_dwordx4 v[72:73], v[56:59], off
	v_lshlrev_b32_e32 v66, 16, v60
	v_and_b32_e32 v67, 0xffff0000, v60
	v_lshlrev_b32_e32 v60, 16, v61
	v_and_b32_e32 v61, 0xffff0000, v61
	v_lshlrev_b32_e32 v68, 16, v62
	v_and_b32_e32 v69, 0xffff0000, v62
	v_lshlrev_b32_e32 v62, 16, v63
	v_and_b32_e32 v63, 0xffff0000, v63
	v_pk_add_f32 v[54:55], v[54:55], v[60:61]
	v_pk_add_f32 v[52:53], v[52:53], v[66:67]
	v_pk_add_f32 v[60:61], v[50:51], v[62:63]
	v_pk_add_f32 v[62:63], v[48:49], v[68:69]
	v_mul_f32_e32 v48, v53, v53
	v_mul_f32_e32 v49, v55, v55
	v_mul_f32_e32 v50, v63, v63
	v_fmac_f32_e32 v48, v52, v52
	v_fmac_f32_e32 v49, v54, v54
	v_mul_f32_e32 v51, v61, v61
	v_fmac_f32_e32 v50, v62, v62
	v_add_f32_e32 v48, v48, v49
	v_add_f32_e32 v48, v50, v48
	v_fmac_f32_e32 v51, v60, v60
	v_add_f32_e32 v48, v51, v48
	v_add_f32_e32 v48, v74, v48
	ds_bpermute_b32 v49, v120, v48
	v_cvt_pk_bf16_f32 v50, v52, v53
	v_cvt_pk_bf16_f32 v51, v54, v55
	v_lshl_add_u64 v[54:55], s[16:17], 0, v[70:71]
	v_cvt_pk_bf16_f32 v52, v62, v63
	s_waitcnt lgkmcnt(0)
	v_add_f32_e32 v48, v48, v49
	ds_bpermute_b32 v49, v114, v48
	v_cvt_pk_bf16_f32 v53, v60, v61
	global_store_dwordx4 v[54:55], v[50:53], off
	s_and_saveexec_b64 s[42:43], s[2:3]
	s_cbranch_execz .LBB0_697
	v_lshl_add_u64 v[50:51], v[64:65], 2, s[18:19]
	s_waitcnt lgkmcnt(0)
	v_add_f32_e32 v48, v48, v49
	global_atomic_add_f32 v[50:51], v48, off
; __device__ __forceinline__ unsigned cvt_pk_bf16(float lo, float hi) { unsigned r; asm volatile("v_cvt_pk_bf16_f32 %0, %1, %2" : "=v"(r) : "v"(lo), "v"(hi)); return r; }
;     __device__ __forceinline__ void operator()(const f32x4 (&acc)[2][2][4][2], const Unit& u, int wr, int wc, int fr, int fq) const {
;         const int row0 = u.pm * BM + wr * 64 + fr; const int col0 = u.pn * BM + wc * 32 + 8 * fq;
; #pragma unroll
;         for (int ai = 0; ai < 2; ++ai)
; #pragma unroll
;             for (int m = 0; m < 4; ++m) { const int row = row0 + ai * HALF + m * 16; const size_t off = (size_t)row * ldc + col0; float part = 0.f;
; #pragma unroll
;                 for (int bj = 0; bj < 2; ++bj) { const size_t idx = off + bj * HALF;
;                     f32x4 b0, b1;
;                     if constexpr (BASE_BF16) { const u32x4 r = *(const u32x4*)(baseb + idx);
;                         b0 = (f32x4){__builtin_bit_cast(float, r.x << 16), __builtin_bit_cast(float, r.x & 0xffff0000u), __builtin_bit_cast(float, r.y << 16), __builtin_bit_cast(float, r.y & 0xffff0000u)};
;                         b1 = (f32x4){__builtin_bit_cast(float, r.z << 16), __builtin_bit_cast(float, r.z & 0xffff0000u), __builtin_bit_cast(float, r.w << 16), __builtin_bit_cast(float, r.w & 0xffff0000u)}; }
;                     else { b0 = *(const f32x4*)(base + idx); b1 = *(const f32x4*)(base + idx + 4); }
;                     const f32x4 o0 = b0 + acc[ai][bj][m][0] * alpha, o1 = b1 + acc[ai][bj][m][1] * alpha;
;                     if constexpr (WRITE_F32) { *(f32x4*)(out + idx) = o0; *(f32x4*)(out + idx + 4) = o1; }
;                     if constexpr (WRITE_XB) {
;                         part += (o0[0] * o0[0] + o0[1] * o0[1]) + (o0[2] * o0[2] + o0[3] * o0[3]) + (o1[0] * o1[0] + o1[1] * o1[1]) + (o1[2] * o1[2] + o1[3] * o1[3]);
;                         u32x4 w; w.x = cvt_pk_bf16(o0[0], o0[1]); w.y = cvt_pk_bf16(o0[2], o0[3]); w.z = cvt_pk_bf16(o1[0], o1[1]); w.w = cvt_pk_bf16(o1[2], o1[3]);
;                         *(u32x4*)(xb + idx) = w; } }
;                 if constexpr (WRITE_XB) { part += __shfl_xor(part, 16); part += __shfl_xor(part, 32);
;                     if (fq == 0) atomicAdd(ss + row, part); } }
;     }
.LBB0_697:
	s_or_b64 exec, exec, s[42:43]
	v_add_u32_e32 v48, 0x90, v146
	s_waitcnt lgkmcnt(0)
	v_ashrrev_i32_e32 v49, 31, v48
	v_lshlrev_b64 v[50:51], 11, v[48:49]
	v_lshl_add_u64 v[50:51], v[50:51], 0, v[144:145]
	v_lshlrev_b64 v[54:55], 1, v[50:51]
	v_lshl_add_u64 v[50:51], s[14:15], 0, v[54:55]
	s_waitcnt vmcnt(5)
	s_nop 1
	v_mov_b32_e32 v50, v212
	v_mov_b32_e32 v51, v213
	v_mov_b32_e32 v52, v214
	v_mov_b32_e32 v53, v215
	v_lshl_add_u64 v[56:57], s[16:17], 0, v[54:55]
	v_or_b32_e32 v54, 0x100, v54
	v_lshl_add_u64 v[58:59], s[14:15], 0, v[54:55]
	v_lshlrev_b32_e32 v60, 16, v50
	v_and_b32_e32 v61, 0xffff0000, v50
	v_lshlrev_b32_e32 v50, 16, v51
	v_and_b32_e32 v51, 0xffff0000, v51
	v_lshlrev_b32_e32 v62, 16, v52
	v_and_b32_e32 v63, 0xffff0000, v52
	v_lshlrev_b32_e32 v52, 16, v53
	v_and_b32_e32 v53, 0xffff0000, v53
	v_pk_add_f32 v[50:51], v[46:47], v[50:51]
	v_pk_add_f32 v[60:61], v[44:45], v[60:61]
	v_pk_add_f32 v[52:53], v[42:43], v[52:53]
	v_pk_add_f32 v[62:63], v[40:41], v[62:63]
	v_cvt_pk_bf16_f32 v40, v60, v61
	v_cvt_pk_bf16_f32 v41, v50, v51
	v_mul_f32_e32 v51, v51, v51
	v_cvt_pk_bf16_f32 v42, v62, v63
	v_cvt_pk_bf16_f32 v43, v52, v53
	s_waitcnt vmcnt(4)
	s_nop 1
	v_mov_b32_e32 v44, v220
	v_mov_b32_e32 v45, v221
	v_mov_b32_e32 v46, v222
	v_mov_b32_e32 v47, v223
	v_mul_f32_e32 v58, v61, v61
	v_mul_f32_e32 v59, v63, v63
	v_fmac_f32_e32 v58, v60, v60
	v_fmac_f32_e32 v51, v50, v50
	v_mul_f32_e32 v53, v53, v53
	v_fmac_f32_e32 v59, v62, v62
	v_add_f32_e32 v50, v58, v51
	v_fmac_f32_e32 v53, v52, v52
	v_add_f32_e32 v50, v59, v50
	v_add_f32_e32 v58, v53, v50
	global_store_dwordx4 v[56:57], v[40:43], off
	v_lshlrev_b32_e32 v50, 16, v44
	v_and_b32_e32 v51, 0xffff0000, v44
	v_lshlrev_b32_e32 v44, 16, v45
	v_and_b32_e32 v45, 0xffff0000, v45
	v_lshlrev_b32_e32 v52, 16, v46
	v_and_b32_e32 v53, 0xffff0000, v46
	v_lshlrev_b32_e32 v46, 16, v47
	v_and_b32_e32 v47, 0xffff0000, v47
	v_pk_add_f32 v[38:39], v[38:39], v[44:45]
	v_pk_add_f32 v[36:37], v[36:37], v[50:51]
	v_pk_add_f32 v[44:45], v[34:35], v[46:47]
	v_pk_add_f32 v[46:47], v[32:33], v[52:53]
	v_mul_f32_e32 v32, v37, v37
	v_mul_f32_e32 v33, v39, v39
	v_mul_f32_e32 v34, v47, v47
	v_fmac_f32_e32 v32, v36, v36
	v_fmac_f32_e32 v33, v38, v38
	v_mul_f32_e32 v35, v45, v45
	v_fmac_f32_e32 v34, v46, v46
	v_add_f32_e32 v32, v32, v33
	v_add_f32_e32 v32, v34, v32
	v_fmac_f32_e32 v35, v44, v44
	v_add_f32_e32 v32, v35, v32
	v_add_f32_e32 v32, v58, v32
	ds_bpermute_b32 v33, v120, v32
	v_cvt_pk_bf16_f32 v34, v36, v37
	v_cvt_pk_bf16_f32 v35, v38, v39
	v_lshl_add_u64 v[38:39], s[16:17], 0, v[54:55]
	v_cvt_pk_bf16_f32 v36, v46, v47
	s_waitcnt lgkmcnt(0)
	v_add_f32_e32 v32, v32, v33
	ds_bpermute_b32 v33, v114, v32
	v_cvt_pk_bf16_f32 v37, v44, v45
	global_store_dwordx4 v[38:39], v[34:37], off
	s_and_saveexec_b64 s[42:43], s[2:3]
	s_cbranch_execz .LBB0_699
	v_lshl_add_u64 v[34:35], v[48:49], 2, s[18:19]
	s_waitcnt lgkmcnt(0)
	v_add_f32_e32 v32, v32, v33
	global_atomic_add_f32 v[34:35], v32, off
; __device__ __forceinline__ unsigned cvt_pk_bf16(float lo, float hi) { unsigned r; asm volatile("v_cvt_pk_bf16_f32 %0, %1, %2" : "=v"(r) : "v"(lo), "v"(hi)); return r; }
;     __device__ __forceinline__ void operator()(const f32x4 (&acc)[2][2][4][2], const Unit& u, int wr, int wc, int fr, int fq) const {
;         const int row0 = u.pm * BM + wr * 64 + fr; const int col0 = u.pn * BM + wc * 32 + 8 * fq;
; #pragma unroll
;         for (int ai = 0; ai < 2; ++ai)
; #pragma unroll
;             for (int m = 0; m < 4; ++m) { const int row = row0 + ai * HALF + m * 16; const size_t off = (size_t)row * ldc + col0; float part = 0.f;
; #pragma unroll
;                 for (int bj = 0; bj < 2; ++bj) { const size_t idx = off + bj * HALF;
;                     f32x4 b0, b1;
;                     if constexpr (BASE_BF16) { const u32x4 r = *(const u32x4*)(baseb + idx);
;                         b0 = (f32x4){__builtin_bit_cast(float, r.x << 16), __builtin_bit_cast(float, r.x & 0xffff0000u), __builtin_bit_cast(float, r.y << 16), __builtin_bit_cast(float, r.y & 0xffff0000u)};
;                         b1 = (f32x4){__builtin_bit_cast(float, r.z << 16), __builtin_bit_cast(float, r.z & 0xffff0000u), __builtin_bit_cast(float, r.w << 16), __builtin_bit_cast(float, r.w & 0xffff0000u)}; }
;                     else { b0 = *(const f32x4*)(base + idx); b1 = *(const f32x4*)(base + idx + 4); }
;                     const f32x4 o0 = b0 + acc[ai][bj][m][0] * alpha, o1 = b1 + acc[ai][bj][m][1] * alpha;
;                     if constexpr (WRITE_F32) { *(f32x4*)(out + idx) = o0; *(f32x4*)(out + idx + 4) = o1; }
;                     if constexpr (WRITE_XB) {
;                         part += (o0[0] * o0[0] + o0[1] * o0[1]) + (o0[2] * o0[2] + o0[3] * o0[3]) + (o1[0] * o1[0] + o1[1] * o1[1]) + (o1[2] * o1[2] + o1[3] * o1[3]);
;                         u32x4 w; w.x = cvt_pk_bf16(o0[0], o0[1]); w.y = cvt_pk_bf16(o0[2], o0[3]); w.z = cvt_pk_bf16(o1[0], o1[1]); w.w = cvt_pk_bf16(o1[2], o1[3]);
;                         *(u32x4*)(xb + idx) = w; } }
;                 if constexpr (WRITE_XB) { part += __shfl_xor(part, 16); part += __shfl_xor(part, 32);
;                     if (fq == 0) atomicAdd(ss + row, part); } }
;     }
.LBB0_699:
	s_or_b64 exec, exec, s[42:43]
	v_add_u32_e32 v32, 0xa0, v146
	s_waitcnt lgkmcnt(0)
	v_ashrrev_i32_e32 v33, 31, v32
	v_lshlrev_b64 v[34:35], 11, v[32:33]
	v_lshl_add_u64 v[34:35], v[34:35], 0, v[144:145]
	v_lshlrev_b64 v[38:39], 1, v[34:35]
	v_lshl_add_u64 v[34:35], s[14:15], 0, v[38:39]
	s_waitcnt vmcnt(3)
	s_nop 1
	v_mov_b32_e32 v34, v224
	v_mov_b32_e32 v35, v225
	v_mov_b32_e32 v36, v226
	v_mov_b32_e32 v37, v227
	v_lshl_add_u64 v[40:41], s[16:17], 0, v[38:39]
	v_or_b32_e32 v38, 0x100, v38
	v_lshl_add_u64 v[42:43], s[14:15], 0, v[38:39]
	v_lshlrev_b32_e32 v44, 16, v34
	v_and_b32_e32 v45, 0xffff0000, v34
	v_lshlrev_b32_e32 v34, 16, v35
	v_and_b32_e32 v35, 0xffff0000, v35
	v_lshlrev_b32_e32 v46, 16, v36
	v_and_b32_e32 v47, 0xffff0000, v36
	v_lshlrev_b32_e32 v36, 16, v37
	v_and_b32_e32 v37, 0xffff0000, v37
	v_pk_add_f32 v[34:35], v[30:31], v[34:35]
	v_pk_add_f32 v[44:45], v[28:29], v[44:45]
	v_pk_add_f32 v[36:37], v[26:27], v[36:37]
	v_pk_add_f32 v[46:47], v[24:25], v[46:47]
	v_cvt_pk_bf16_f32 v24, v44, v45
	v_cvt_pk_bf16_f32 v25, v34, v35
	v_mul_f32_e32 v35, v35, v35
	v_cvt_pk_bf16_f32 v26, v46, v47
	v_cvt_pk_bf16_f32 v27, v36, v37
	s_waitcnt vmcnt(2)
	s_nop 1
	v_mov_b32_e32 v28, v228
	v_mov_b32_e32 v29, v229
	v_mov_b32_e32 v30, v230
	v_mov_b32_e32 v31, v231
	v_mul_f32_e32 v42, v45, v45
	v_mul_f32_e32 v43, v47, v47
	v_fmac_f32_e32 v42, v44, v44
	v_fmac_f32_e32 v35, v34, v34
	v_mul_f32_e32 v37, v37, v37
	v_fmac_f32_e32 v43, v46, v46
	v_add_f32_e32 v34, v42, v35
	v_fmac_f32_e32 v37, v36, v36
	v_add_f32_e32 v34, v43, v34
	v_add_f32_e32 v42, v37, v34
	global_store_dwordx4 v[40:41], v[24:27], off
	v_lshlrev_b32_e32 v34, 16, v28
	v_and_b32_e32 v35, 0xffff0000, v28
	v_lshlrev_b32_e32 v28, 16, v29
	v_and_b32_e32 v29, 0xffff0000, v29
	v_lshlrev_b32_e32 v36, 16, v30
	v_and_b32_e32 v37, 0xffff0000, v30
	v_lshlrev_b32_e32 v30, 16, v31
	v_and_b32_e32 v31, 0xffff0000, v31
	v_pk_add_f32 v[22:23], v[22:23], v[28:29]
	v_pk_add_f32 v[20:21], v[20:21], v[34:35]
	v_pk_add_f32 v[28:29], v[18:19], v[30:31]
	v_pk_add_f32 v[30:31], v[16:17], v[36:37]
	v_mul_f32_e32 v16, v21, v21
	v_mul_f32_e32 v17, v23, v23
	v_mul_f32_e32 v18, v31, v31
	v_fmac_f32_e32 v16, v20, v20
	v_fmac_f32_e32 v17, v22, v22
	v_mul_f32_e32 v19, v29, v29
	v_fmac_f32_e32 v18, v30, v30
	v_add_f32_e32 v16, v16, v17
	v_add_f32_e32 v16, v18, v16
	v_fmac_f32_e32 v19, v28, v28
	v_add_f32_e32 v16, v19, v16
	v_add_f32_e32 v16, v42, v16
	ds_bpermute_b32 v17, v120, v16
	v_cvt_pk_bf16_f32 v18, v20, v21
	v_cvt_pk_bf16_f32 v19, v22, v23
	v_lshl_add_u64 v[22:23], s[16:17], 0, v[38:39]
	v_cvt_pk_bf16_f32 v20, v30, v31
	s_waitcnt lgkmcnt(0)
	v_add_f32_e32 v16, v16, v17
	ds_bpermute_b32 v17, v114, v16
	v_cvt_pk_bf16_f32 v21, v28, v29
	global_store_dwordx4 v[22:23], v[18:21], off
	s_and_saveexec_b64 s[42:43], s[2:3]
	s_cbranch_execz .LBB0_701
	v_lshl_add_u64 v[18:19], v[32:33], 2, s[18:19]
	s_waitcnt lgkmcnt(0)
	v_add_f32_e32 v16, v16, v17
	global_atomic_add_f32 v[18:19], v16, off
.LBB0_701:
	s_or_b64 exec, exec, s[42:43]
	v_add_u32_e32 v16, 0xb0, v146
	s_waitcnt lgkmcnt(0)
	v_ashrrev_i32_e32 v17, 31, v16
	v_lshlrev_b64 v[18:19], 11, v[16:17]
	v_lshl_add_u64 v[18:19], v[18:19], 0, v[144:145]
	v_lshlrev_b64 v[22:23], 1, v[18:19]
	v_lshl_add_u64 v[18:19], s[14:15], 0, v[22:23]
	s_waitcnt vmcnt(1)
	s_nop 1
	v_mov_b32_e32 v18, v232
	v_mov_b32_e32 v19, v233
	v_mov_b32_e32 v20, v234
	v_mov_b32_e32 v21, v235
	v_lshl_add_u64 v[24:25], s[16:17], 0, v[22:23]
	v_or_b32_e32 v22, 0x100, v22
	v_lshl_add_u64 v[26:27], s[14:15], 0, v[22:23]
	v_lshlrev_b32_e32 v28, 16, v18
	v_and_b32_e32 v29, 0xffff0000, v18
	v_lshlrev_b32_e32 v18, 16, v19
	v_and_b32_e32 v19, 0xffff0000, v19
	v_lshlrev_b32_e32 v30, 16, v20
	v_and_b32_e32 v31, 0xffff0000, v20
	v_lshlrev_b32_e32 v20, 16, v21
	v_and_b32_e32 v21, 0xffff0000, v21
	v_pk_add_f32 v[18:19], v[14:15], v[18:19]
	v_pk_add_f32 v[28:29], v[12:13], v[28:29]
	v_pk_add_f32 v[20:21], v[10:11], v[20:21]
	v_pk_add_f32 v[30:31], v[8:9], v[30:31]
	v_cvt_pk_bf16_f32 v8, v28, v29
	v_cvt_pk_bf16_f32 v9, v18, v19
	v_mul_f32_e32 v19, v19, v19
	v_cvt_pk_bf16_f32 v10, v30, v31
	v_cvt_pk_bf16_f32 v11, v20, v21
	s_waitcnt vmcnt(0)
	s_nop 1
	v_mov_b32_e32 v12, v236
	v_mov_b32_e32 v13, v237
	v_mov_b32_e32 v14, v238
	v_mov_b32_e32 v15, v239
	v_mul_f32_e32 v26, v29, v29
	v_mul_f32_e32 v27, v31, v31
	v_fmac_f32_e32 v26, v28, v28
	v_fmac_f32_e32 v19, v18, v18
	v_mul_f32_e32 v21, v21, v21
	v_fmac_f32_e32 v27, v30, v30
	v_add_f32_e32 v18, v26, v19
	v_fmac_f32_e32 v21, v20, v20
	v_add_f32_e32 v18, v27, v18
	v_add_f32_e32 v26, v21, v18
	global_store_dwordx4 v[24:25], v[8:11], off
	v_lshlrev_b32_e32 v18, 16, v12
	v_and_b32_e32 v19, 0xffff0000, v12
	v_lshlrev_b32_e32 v12, 16, v13
	v_and_b32_e32 v13, 0xffff0000, v13
	v_lshlrev_b32_e32 v20, 16, v14
	v_and_b32_e32 v21, 0xffff0000, v14
	v_lshlrev_b32_e32 v14, 16, v15
	v_and_b32_e32 v15, 0xffff0000, v15
	v_pk_add_f32 v[6:7], v[6:7], v[12:13]
	v_pk_add_f32 v[4:5], v[4:5], v[18:19]
	v_pk_add_f32 v[12:13], v[2:3], v[14:15]
	v_pk_add_f32 v[14:15], v[0:1], v[20:21]
	v_mul_f32_e32 v0, v5, v5
	v_mul_f32_e32 v1, v7, v7
	v_mul_f32_e32 v2, v15, v15
	v_fmac_f32_e32 v0, v4, v4
	v_fmac_f32_e32 v1, v6, v6
	v_mul_f32_e32 v3, v13, v13
	v_fmac_f32_e32 v2, v14, v14
	v_add_f32_e32 v0, v0, v1
	v_add_f32_e32 v0, v2, v0
	v_fmac_f32_e32 v3, v12, v12
	v_add_f32_e32 v0, v3, v0
	v_add_f32_e32 v0, v26, v0
	ds_bpermute_b32 v1, v120, v0
	v_cvt_pk_bf16_f32 v2, v4, v5
	v_cvt_pk_bf16_f32 v3, v6, v7
	v_lshl_add_u64 v[6:7], s[16:17], 0, v[22:23]
	v_cvt_pk_bf16_f32 v4, v14, v15
	s_waitcnt lgkmcnt(0)
	v_add_f32_e32 v0, v0, v1
	ds_bpermute_b32 v1, v114, v0
	v_cvt_pk_bf16_f32 v5, v12, v13
	global_store_dwordx4 v[6:7], v[2:5], off
	s_and_saveexec_b64 s[42:43], s[2:3]
	s_cbranch_execz .LBB0_703
	v_lshl_add_u64 v[2:3], v[16:17], 2, s[18:19]
	s_waitcnt lgkmcnt(0)
	v_add_f32_e32 v0, v0, v1
	global_atomic_add_f32 v[2:3], v0, off
